# RG-LRU final pass: wave owns 16 output channels for all 64 tokens, W_r/W_i fragments resident in VGPRs for the whole phase (no per-item W loads); same MFMA shapes and op order
# speedup vs baseline: 1.0555x; 1.0188x over previous
; __device__ __forceinline__ int TIDX() { int t = threadIdx.x; asm volatile("" : "+v"(t)); return t; }
; __device__ __forceinline__ int BIDX() { int b = blockIdx.x; asm volatile("" : "+s"(b)); return b; }
; template <bool FINAL>
; __device__ void phase_lru(const Params& p, int l, unsigned char* smem) {
;   u16* xs = (u16*)smem;
;   float* u32 = (float*)(smem + 8704);
;   u16* ub = (u16*)(smem + 25088);
;   float* sa = (float*)(smem + 34304);
;   float* sb = (float*)(smem + 50688);
;   float* part = (float*)(smem + 67072);
;   const int tid = TIDX(), lane = tid & 63, w = tid >> 6, l15 = lane & 15, g = lane >> 4;
;   const int e_ = tid & 63, qd = tid >> 6;
;   const int NIT = NCHUNK * 8;
;   const int step = gridDim.x;
;   int it = BIDX();
;   uint4 x0 = make_uint4(0, 0, 0, 0), x1 = x0, x2 = x0;
;     ...
;           const u16* wr = p.WLRU + ((((size_t)(l * 2 + d) * 2 + 0) * 8 + nb) * 64 + et * 16 + l15) * 64 + g * 8;
;           const u16* wi = p.WLRU + ((((size_t)(l * 2 + d) * 2 + 1) * 8 + nb) * 64 + et * 16 + l15) * 64 + g * 8;
; #pragma unroll
;           for (int ks = 0; ks < 2; ++ks) {
;             ar = mfma16(*(const bf16x8*)(wr + ks * 32), uf[ks], ar);
;             ai = mfma16(*(const bf16x8*)(wi + ks * 32), uf[ks], ai);
;           }
;           const int e0 = et * 16 + 4 * g, ch0 = nb * 64 + e0;
;           const float4 ba4 = *(const float4*)(p.ba + (l * 2 + d) * 512 + ch0);
;           const float4 bx4 = *(const float4*)(p.bx + (l * 2 + d) * 512 + ch0);
;           const float4 sp4 = *(const float4*)(p.SP8 + (l * 2 + d) * 512 + ch0);
.LBB0_196:
	s_mov_b32 s4, s22
	s_andn2_b64 vcc, exec, s[30:31]
	v_writelane_b32 v248, s4, 38
	s_nop 1
	v_writelane_b32 v248, s5, 39
	s_cbranch_vccnz .LBB0_226
	v_and_b32_e32 v38, 63, v12
	v_ashrrev_i32_e32 v13, 6, v12
	v_lshlrev_b32_e32 v17, 1, v38
	v_and_b32_e32 v39, 15, v12
	v_add_u32_e32 v18, 0, v17
	v_lshlrev_b32_e32 v21, 4, v13
	v_bfe_u32 v16, v12, 4, 2
	v_add_u32_e32 v20, 0x100, v12
	v_add_u32_e32 v96, v18, v17
	v_or_b32_e32 v17, v21, v39
	v_ashrrev_i32_e32 v51, 3, v20
	v_add_u32_e32 v20, 0x200, v12
	v_mul_lo_u32 v22, v17, s28
	v_lshlrev_b32_e32 v50, 3, v16
	v_and_b32_e32 v23, 48, v12
	v_lshlrev_b32_e32 v97, 2, v16
	v_readlane_b32 s4, v248, 16
	v_lshlrev_b32_e32 v16, 2, v38
	v_lshlrev_b32_e32 v14, 3, v12
	v_ashrrev_i32_e32 v53, 3, v20
	v_add3_u32 v52, 0, v22, v23
	v_lshl_add_u32 v98, v12, 2, s4
	v_add_u32_e32 v99, s4, v16
	s_movk_i32 s4, 0x70
	v_and_b32_e32 v40, 56, v14
	v_add_u32_e32 v14, 32, v36
	v_mad_u64_u32 v[58:59], s[42:43], v17, s4, v[52:53]
	v_readlane_b32 s4, v248, 17
	v_mad_i64_i32 v[42:43], s[30:31], v36, s26, 0
	v_mad_i64_i32 v[44:45], s[30:31], v14, s26, 0
	v_mad_i64_i32 v[46:47], s[30:31], v51, s26, 0
	v_mad_i64_i32 v[48:49], s[30:31], v53, s26, 0
	v_add_u32_e32 v133, s4, v16
	v_readlane_b32 s4, v248, 18
	v_lshlrev_b32_e32 v15, 4, v12
	s_lshl_b32 s30, s22, 1
	v_add_u32_e32 v134, s4, v16
	v_readlane_b32 s4, v248, 19
	v_and_b32_e32 v15, 0xffffff80, v15
	v_lshlrev_b32_e32 v19, 1, v40
	s_or_b32 s56, s30, 1
	v_add_u32_e32 v135, s4, v16
	v_readlane_b32 s4, v248, 20
	v_add3_u32 v41, 0, v15, v19
	v_cmp_gt_i32_e64 s[38:39], 24, v12
	v_ashrrev_i32_e32 v15, 31, v14
	v_and_b32_e32 v12, 0x3fffffc0, v12
	s_ashr_i32 s31, s30, 31
	s_lshl_b32 s40, s22, 10
	s_lshl_b32 s66, s56, 9
	v_add_u32_e32 v136, s4, v16
	v_readlane_b32 s4, v250, 5
	s_lshl_b32 s58, s22, 11
	s_lshl_b32 s59, s22, 9
	v_lshl_add_u32 v100, v12, 2, v99
	v_mul_lo_u32 v12, v36, s28
	v_lshlrev_b64 v[56:57], 11, v[14:15]
	v_lshlrev_b32_e32 v102, 12, v13
	v_or_b32_e32 v14, 1, v21
	s_ashr_i32 s41, s40, 31
	s_ashr_i32 s57, s56, 31
	s_ashr_i32 s67, s66, 31
	s_lshl_b64 s[30:31], s[30:31], 17
	v_readlane_b32 s10, v250, 11
	v_ashrrev_i32_e32 v37, 31, v36
	v_add3_u32 v12, 0, v12, v19
	v_lshlrev_b32_e32 v103, 8, v14
	v_or_b32_e32 v19, 2, v21
	v_or_b32_e32 v17, v102, v16
	v_readlane_b32 s11, v250, 12
	v_readlane_b32 s16, v250, 17
	v_readlane_b32 s17, v250, 18
	v_readlane_b32 s18, v250, 19
	v_readlane_b32 s19, v250, 20
	s_add_u32 s42, s10, s30
	v_add_u32_e32 v101, 0x6200, v12
	v_lshlrev_b64 v[54:55], 11, v[36:37]
	v_add_u32_e32 v37, 0x7400, v12
	v_mul_lo_u32 v12, v13, s27
	v_mul_lo_u32 v15, v14, s28
	v_lshlrev_b32_e32 v104, 8, v19
	v_or_b32_e32 v22, 3, v21
	v_add_u32_e32 v59, 0, v17
	v_or_b32_e32 v17, v103, v16
	s_addc_u32 s43, s11, s31
	v_readlane_b32 s16, v250, 37
	v_lshlrev_b32_e32 v105, 8, v22
	v_or_b32_e32 v23, 4, v21
	v_add_u32_e32 v118, 0, v17
	v_or_b32_e32 v17, v104, v16
	s_lshl_b64 s[40:41], s[40:41], 2
	v_readlane_b32 s20, v250, 41
	v_readlane_b32 s24, v250, 45
	v_lshlrev_b32_e32 v106, 8, v23
	v_or_b32_e32 v24, 5, v21
	v_add_u32_e32 v119, 0, v17
	v_or_b32_e32 v17, v105, v16
	v_readlane_b32 s21, v250, 42
	v_readlane_b32 s25, v250, 46
	s_mov_b32 s20, s58
	s_add_u32 s58, s24, s40
	v_lshlrev_b32_e32 v107, 8, v24
	v_or_b32_e32 v25, 6, v21
	v_add_u32_e32 v120, 0, v17
	v_or_b32_e32 v17, v106, v16
	v_cmp_lt_i32_e64 s[60:61], 0, v13
	v_readlane_b32 s22, v250, 43
	v_readlane_b32 s23, v250, 44
	v_readlane_b32 s28, v250, 49
	s_mov_b32 s21, s59
	s_addc_u32 s59, s25, s41
	v_lshlrev_b32_e32 v108, 8, v25
	v_or_b32_e32 v26, 7, v21
	v_add_u32_e32 v121, 0, v17
	v_or_b32_e32 v17, v107, v16
	v_readlane_b32 s29, v250, 50
	s_mov_b64 s[22:23], s[60:61]
	s_add_u32 s60, s28, s40
	v_lshlrev_b32_e32 v109, 8, v26
	v_or_b32_e32 v27, 8, v21
	v_add_u32_e32 v122, 0, v17
	v_or_b32_e32 v17, v108, v16
	v_readlane_b32 s14, v250, 15
	s_addc_u32 s61, s29, s41
	v_lshlrev_b32_e32 v110, 8, v27
	v_or_b32_e32 v28, 9, v21
	v_add_u32_e32 v123, 0, v17
	v_or_b32_e32 v17, v109, v16
	v_readlane_b32 s15, v250, 16
	s_add_u32 s62, s14, s40
	v_lshlrev_b32_e32 v111, 8, v28
	v_or_b32_e32 v29, 10, v21
	v_add_u32_e32 v124, 0, v17
	v_or_b32_e32 v17, v110, v16
	s_addc_u32 s63, s15, s41
	s_lshl_b64 s[40:41], s[56:57], 17
; template <bool FINAL>
; __device__ void phase_lru(const Params& p, int l, unsigned char* smem) {
;     ...
;         const int t = 16 * w + l15;
; #pragma unroll
;         for (int et = 0; et < 4; ++et) {
;           f32x4 ar = {0.f, 0.f, 0.f, 0.f}, ai = {0.f, 0.f, 0.f, 0.f};
;           const u16* wr = p.WLRU + ((((size_t)(l * 2 + d) * 2 + 0) * 8 + nb) * 64 + et * 16 + l15) * 64 + g * 8;
;           const u16* wi = p.WLRU + ((((size_t)(l * 2 + d) * 2 + 1) * 8 + nb) * 64 + et * 16 + l15) * 64 + g * 8;
; #pragma unroll
;           for (int ks = 0; ks < 2; ++ks) {
;             ar = mfma16(*(const bf16x8*)(wr + ks * 32), uf[ks], ar);
;             ai = mfma16(*(const bf16x8*)(wi + ks * 32), uf[ks], ai);
;           }
;           const int e0 = et * 16 + 4 * g, ch0 = nb * 64 + e0;
;           const float4 ba4 = *(const float4*)(p.ba + (l * 2 + d) * 512 + ch0);
;           const float4 bx4 = *(const float4*)(p.bx + (l * 2 + d) * 512 + ch0);
;           const float4 sp4 = *(const float4*)(p.SP8 + (l * 2 + d) * 512 + ch0);
	v_lshlrev_b32_e32 v112, 8, v29
	v_or_b32_e32 v30, 11, v21
	v_add_u32_e32 v125, 0, v17
	v_or_b32_e32 v17, v111, v16
	s_add_u32 s64, s10, s40
	v_lshlrev_b32_e32 v113, 8, v30
	v_or_b32_e32 v31, 12, v21
	v_add_u32_e32 v126, 0, v17
	v_or_b32_e32 v17, v112, v16
	s_addc_u32 s65, s11, s41
	s_lshl_b64 s[40:41], s[66:67], 2
	v_lshlrev_b32_e32 v114, 8, v31
	v_or_b32_e32 v32, 13, v21
	v_add_u32_e32 v127, 0, v17
	v_or_b32_e32 v17, v113, v16
	s_add_u32 s66, s24, s40
	v_lshlrev_b32_e32 v115, 8, v32
	v_or_b32_e32 v33, 14, v21
	v_add_u32_e32 v128, 0, v17
	v_or_b32_e32 v17, v114, v16
	v_cmp_lt_i32_e64 s[68:69], 1, v13
	s_addc_u32 s67, s25, s41
	v_lshlrev_b32_e32 v116, 8, v33
	v_or_b32_e32 v21, 15, v21
	v_add_u32_e32 v129, 0, v17
	v_or_b32_e32 v17, v115, v16
	s_mov_b64 s[24:25], s[68:69]
	s_add_u32 s68, s28, s40
	v_lshlrev_b32_e32 v117, 8, v21
	v_add_u32_e32 v130, 0, v17
	v_or_b32_e32 v17, v116, v16
	v_readlane_b32 s5, v250, 6
	s_addc_u32 s69, s29, s41
	v_add_u32_e32 v131, 0, v17
	v_or_b32_e32 v17, v117, v16
	s_add_u32 s72, s14, s40
	v_readlane_b32 s4, v250, 1
	v_lshlrev_b32_e32 v20, 11, v13
	v_add_u32_e32 v132, 0, v17
	v_cmp_lt_i32_e64 s[44:45], 2, v13
	v_cmp_lt_i32_e64 s[46:47], 3, v13
	v_cmp_gt_i32_e64 s[48:49], 3, v13
	v_cmp_gt_i32_e64 s[50:51], 2, v13
	v_cmp_gt_i32_e64 s[52:53], 1, v13
	v_cmp_gt_i32_e64 s[54:55], 0, v13
	v_lshlrev_b32_e32 v13, 7, v14
	v_lshlrev_b32_e32 v14, 7, v19
	v_lshlrev_b32_e32 v16, 7, v22
	v_lshlrev_b32_e32 v17, 7, v23
	v_lshlrev_b32_e32 v19, 7, v24
	v_lshlrev_b32_e32 v22, 7, v25
	v_lshlrev_b32_e32 v23, 7, v26
	v_lshlrev_b32_e32 v24, 7, v27
	v_lshlrev_b32_e32 v25, 7, v28
	v_lshlrev_b32_e32 v26, 7, v29
	v_lshlrev_b32_e32 v27, 7, v30
	v_lshlrev_b32_e32 v28, 7, v31
	v_lshlrev_b32_e32 v29, 7, v32
	v_lshlrev_b32_e32 v30, 7, v33
	v_lshlrev_b32_e32 v21, 7, v21
	s_addc_u32 s73, s15, s41
	s_add_i32 s40, s4, s36
	s_lshl_b32 s99, s40, 3
	s_lshl_b32 s97, s36, 6
	v_lshlrev_b32_e32 v137, 2, v38
	v_add_u32_e32 v138, v18, v13
	v_add_u32_e32 v139, v18, v14
	v_add_u32_e32 v140, v18, v16
	v_add_u32_e32 v141, v18, v17
	v_add_u32_e32 v142, v18, v19
	v_add_u32_e32 v143, v18, v22
	v_add_u32_e32 v149, v18, v23
	v_add_u32_e32 v150, v18, v24
	v_add_u32_e32 v151, v18, v25
	v_add_u32_e32 v152, v18, v26
	v_add_u32_e32 v153, v18, v27
	v_add_u32_e32 v154, v18, v28
	v_add_u32_e32 v155, v18, v29
	v_add_u32_e32 v156, v18, v30
	v_add_u32_e32 v157, v18, v21
	v_add_u32_e32 v158, v18, v20
	v_add_u32_e32 v159, v18, v12
	v_add_u32_e32 v160, v18, v15
	v_readlane_b32 s6, v250, 7
	v_readlane_b32 s7, v250, 8
	v_readlane_b32 s8, v250, 9
	v_readlane_b32 s9, v250, 10
	v_readlane_b32 s12, v250, 13
	v_readlane_b32 s13, v250, 14
	v_readlane_b32 s17, v250, 38
	v_readlane_b32 s18, v250, 39
	v_readlane_b32 s19, v250, 40
	v_readlane_b32 s26, v250, 47
	v_readlane_b32 s27, v250, 48
	v_readlane_b32 s30, v250, 51
	v_readlane_b32 s31, v250, 52
	v_readlane_b32 s5, v250, 2
	s_lshl_b32 s32, s36, 6
	s_and_b32 s32, s32, 0x1c0
	v_lshrrev_b32_e32 v12, 6, v147
	v_and_b32_e32 v22, 15, v147
	v_lshlrev_b32_e32 v13, 4, v12
	v_or_b32_e32 v13, v13, v22
	v_or_b32_e32 v13, s32, v13
	v_lshlrev_b32_e32 v14, 7, v13
	v_mov_b32_e32 v15, v145
	v_bfe_u32 v16, v147, 4, 2
	v_lshlrev_b32_e32 v17, 4, v16
	v_add_u32_e32 v14, v14, v17
	v_lshl_add_u64 v[18:19], s[42:43], 0, v[14:15]
	global_load_dwordx4 v[180:183], v[18:19], off
	global_load_dwordx4 v[184:187], v[18:19], off offset:64
	v_add_co_u32_e32 v20, vcc, 0x10000, v18
	s_nop 0
	v_addc_co_u32_e32 v21, vcc, 0, v19, vcc
	global_load_dwordx4 v[188:191], v[20:21], off
	global_load_dwordx4 v[192:195], v[20:21], off offset:64
	v_lshl_add_u64 v[18:19], s[64:65], 0, v[14:15]
	global_load_dwordx4 v[232:235], v[18:19], off
	global_load_dwordx4 v[236:239], v[18:19], off offset:64
	v_add_co_u32_e32 v20, vcc, 0x10000, v18
	s_nop 0
	v_addc_co_u32_e32 v21, vcc, 0, v19, vcc
	global_load_dwordx4 v[240:243], v[20:21], off
	global_load_dwordx4 v[244:247], v[20:21], off offset:64
	v_mul_u32_u24_e32 v229, 0x90, v22
	v_add_u32_e32 v229, v229, v17
	v_lshlrev_b32_e32 v230, 8, v22
	v_add_u32_e32 v230, v230, v17
	v_lshl_add_u32 v230, v12, 6, v230
	v_lshlrev_b32_e32 v231, 4, v12
	v_lshl_add_u32 v231, v16, 2, v231
	v_or_b32_e32 v231, s32, v231
	v_lshlrev_b32_e32 v231, 2, v231
	s_branch .LBB0_199

; __device__ __forceinline__ float bf2f(unsigned h) { return __uint_as_float(h << 16); }
; template <bool FINAL>
; __device__ void phase_lru(const Params& p, int l, unsigned char* smem) {
;     ...
;     if (it + step < NIT) load_x(it + step, x0, x1, x2);
;     {
;       const int ch = nb * 64 + e_;
;       const float cw0 = p.conv_w[(l * 4 + 0) * 512 + ch], cw1 = p.conv_w[(l * 4 + 1) * 512 + ch],
;                   cw2 = p.conv_w[(l * 4 + 2) * 512 + ch], cw3 = p.conv_w[(l * 4 + 3) * 512 + ch];
;       const float cb = p.conv_b[l * 512 + ch];
;       float xv[19];
; #pragma unroll
;       for (int k = 0; k < 19; ++k) xv[k] = bf2f(xs[(qd * 16 + k) * 64 + e_]);
; #pragma unroll
;       for (int tt = 0; tt < 16; ++tt) {
;         const int t = qd * 16 + tt;
;         const float u = cb + xv[tt] * cw0 + xv[tt + 1] * cw1 + xv[tt + 2] * cw2 + xv[tt + 3] * cw3;
;         u32[t * 64 + e_] = u;
;         ub[t * 72 + e_] = (u16)f2bf(u);
;       }
;     }
.LBB0_209:
	v_or_b32_e32 v26, s40, v38
	v_or_b32_e32 v20, s20, v26
	v_readlane_b32 s4, v250, 37
	v_ashrrev_i32_e32 v21, 31, v20
	v_readlane_b32 s6, v250, 39
	v_readlane_b32 s7, v250, 40
	v_readlane_b32 s8, v250, 41
	v_readlane_b32 s9, v250, 42
	v_lshl_add_u64 v[22:23], v[20:21], 2, s[6:7]
	v_add_co_u32_e32 v24, vcc, 0x1000, v22
	global_load_dword v21, v[22:23], off
	global_load_dword v20, v[22:23], off offset:2048
	v_addc_co_u32_e32 v25, vcc, 0, v23, vcc
	global_load_dword v23, v[24:25], off
	global_load_dword v22, v[24:25], off offset:2048
	v_or_b32_e32 v24, s21, v26
	v_ashrrev_i32_e32 v25, 31, v24
	v_lshl_add_u64 v[24:25], v[24:25], 2, s[8:9]
	global_load_dword v24, v[24:25], off
	ds_read_u16 v25, v158
	ds_read_u16 v26, v158 offset:128
	ds_read_u16 v27, v158 offset:256
	ds_read_u16 v28, v158 offset:384
	ds_read_u16 v29, v158 offset:512
	s_waitcnt lgkmcnt(4)
	v_lshlrev_b32_e32 v25, 16, v25
	s_waitcnt lgkmcnt(3)
	v_lshlrev_b32_e32 v26, 16, v26
	s_waitcnt lgkmcnt(2)
	v_lshlrev_b32_e32 v27, 16, v27
	s_waitcnt lgkmcnt(1)
	v_lshlrev_b32_e32 v28, 16, v28
	v_add_u32_e32 v69, v96, v102
	ds_read_u16 v30, v158 offset:640
	ds_read_u16 v31, v158 offset:768
	ds_read_u16 v32, v158 offset:896
	ds_read_u16 v33, v158 offset:1024
	ds_read_u16 v34, v158 offset:1152
	ds_read_u16 v35, v158 offset:1280
	ds_read_u16 v61, v158 offset:1408
	ds_read_u16 v62, v158 offset:1536
	ds_read_u16 v63, v158 offset:1664
	ds_read_u16 v64, v158 offset:1792
	ds_read_u16 v65, v158 offset:1920
	ds_read_u16 v66, v158 offset:2048
	ds_read_u16 v67, v158 offset:2176
	ds_read_u16 v68, v158 offset:2304
	s_waitcnt lgkmcnt(14)
	v_lshlrev_b32_e32 v29, 16, v29
	s_waitcnt lgkmcnt(13)
	v_lshlrev_b32_e32 v30, 16, v30
	s_waitcnt lgkmcnt(12)
	v_lshlrev_b32_e32 v31, 16, v31
	s_waitcnt lgkmcnt(11)
	v_lshlrev_b32_e32 v32, 16, v32
	s_waitcnt lgkmcnt(10)
	v_lshlrev_b32_e32 v33, 16, v33
	s_waitcnt lgkmcnt(9)
	v_lshlrev_b32_e32 v34, 16, v34
	s_waitcnt lgkmcnt(8)
	v_lshlrev_b32_e32 v35, 16, v35
	s_waitcnt lgkmcnt(7)
	v_lshlrev_b32_e32 v61, 16, v61
	s_waitcnt lgkmcnt(6)
	v_lshlrev_b32_e32 v62, 16, v62
	s_waitcnt lgkmcnt(5)
	v_lshlrev_b32_e32 v63, 16, v63
	s_waitcnt lgkmcnt(4)
	v_lshlrev_b32_e32 v64, 16, v64
	s_waitcnt lgkmcnt(3)
	v_lshlrev_b32_e32 v65, 16, v65
	s_waitcnt lgkmcnt(2)
	v_lshlrev_b32_e32 v66, 16, v66
	s_waitcnt lgkmcnt(1)
	v_lshlrev_b32_e32 v67, 16, v67
	s_waitcnt lgkmcnt(0)
	v_lshlrev_b32_e32 v68, 16, v68
	v_readlane_b32 s5, v250, 38
	s_mov_b64 s[4:5], 0x10000
	s_mov_b32 s6, 0xbe800000
	s_mov_b64 s[8:9], 0x10800
	s_ashr_i32 s93, s92, 31
	v_readlane_b32 s10, v250, 43
	v_readlane_b32 s11, v250, 44
	v_readlane_b32 s12, v250, 45
	v_readlane_b32 s13, v250, 46
	v_readlane_b32 s14, v250, 47
	v_readlane_b32 s15, v250, 48
	v_readlane_b32 s16, v250, 49
	v_readlane_b32 s17, v250, 50
	v_readlane_b32 s18, v250, 51
	v_readlane_b32 s19, v250, 52
	s_waitcnt vmcnt(0)
	v_fma_f32 v25, v21, v25, v24
	v_fmac_f32_e32 v25, v20, v26
	v_fmac_f32_e32 v25, v23, v27
	v_fmac_f32_e32 v25, v22, v28
	ds_write_b32 v69, v25 offset:8704
	v_cvt_pk_bf16_f32 v25, v25, s0
	ds_write_b16 v159, v25 offset:25088
	v_fma_f32 v25, v21, v26, v24
	v_fmac_f32_e32 v25, v20, v27
	v_fmac_f32_e32 v25, v23, v28
	v_fmac_f32_e32 v25, v22, v29
	v_add_u32_e32 v26, v96, v103
	ds_write_b32 v26, v25 offset:8704
	v_cvt_pk_bf16_f32 v25, v25, s0
	ds_write_b16 v160, v25 offset:25088
	v_fma_f32 v25, v21, v27, v24
	v_fmac_f32_e32 v25, v20, v28
	v_fmac_f32_e32 v25, v23, v29
	v_fmac_f32_e32 v25, v22, v30
	v_add_u32_e32 v26, v96, v104
	ds_write_b32 v26, v25 offset:8704
	v_cvt_pk_bf16_f32 v25, v25, s0
	ds_write_b16 v160, v25 offset:25232
	v_fma_f32 v25, v21, v28, v24
	v_fmac_f32_e32 v25, v20, v29
	v_fmac_f32_e32 v25, v23, v30
	v_fmac_f32_e32 v25, v22, v31
	v_add_u32_e32 v26, v96, v105
	ds_write_b32 v26, v25 offset:8704
	v_cvt_pk_bf16_f32 v25, v25, s0
	ds_write_b16 v160, v25 offset:25376
	v_fma_f32 v25, v21, v29, v24
	v_fmac_f32_e32 v25, v20, v30
	v_fmac_f32_e32 v25, v23, v31
	v_fmac_f32_e32 v25, v22, v32
	v_add_u32_e32 v26, v96, v106
	ds_write_b32 v26, v25 offset:8704
	v_cvt_pk_bf16_f32 v25, v25, s0
	ds_write_b16 v160, v25 offset:25520
	v_fma_f32 v25, v21, v30, v24
	v_fmac_f32_e32 v25, v20, v31
	v_fmac_f32_e32 v25, v23, v32
	v_fmac_f32_e32 v25, v22, v33
	v_add_u32_e32 v26, v96, v107
	ds_write_b32 v26, v25 offset:8704
	v_cvt_pk_bf16_f32 v25, v25, s0
	ds_write_b16 v160, v25 offset:25664
	v_fma_f32 v25, v21, v31, v24
	v_fmac_f32_e32 v25, v20, v32
	v_fmac_f32_e32 v25, v23, v33
	v_fmac_f32_e32 v25, v22, v34
	v_add_u32_e32 v26, v96, v108
	ds_write_b32 v26, v25 offset:8704
	v_cvt_pk_bf16_f32 v25, v25, s0
	ds_write_b16 v160, v25 offset:25808
	v_fma_f32 v25, v21, v32, v24
	v_fmac_f32_e32 v25, v20, v33
	v_fmac_f32_e32 v25, v23, v34
	v_fmac_f32_e32 v25, v22, v35
	v_add_u32_e32 v26, v96, v109
	ds_write_b32 v26, v25 offset:8704
	v_cvt_pk_bf16_f32 v25, v25, s0
	ds_write_b16 v160, v25 offset:25952
	v_fma_f32 v25, v21, v33, v24
	v_fmac_f32_e32 v25, v20, v34
	v_fmac_f32_e32 v25, v23, v35
	v_fmac_f32_e32 v25, v22, v61
	v_add_u32_e32 v26, v96, v110
	ds_write_b32 v26, v25 offset:8704
	v_cvt_pk_bf16_f32 v25, v25, s0
	ds_write_b16 v160, v25 offset:26096
	v_fma_f32 v25, v21, v34, v24
	v_fmac_f32_e32 v25, v20, v35
	v_fmac_f32_e32 v25, v23, v61
	v_fmac_f32_e32 v25, v22, v62
	v_add_u32_e32 v26, v96, v111
	ds_write_b32 v26, v25 offset:8704
	v_cvt_pk_bf16_f32 v25, v25, s0
	ds_write_b16 v160, v25 offset:26240
	v_fma_f32 v25, v21, v35, v24
	v_fmac_f32_e32 v25, v20, v61
	v_fmac_f32_e32 v25, v23, v62
	v_fmac_f32_e32 v25, v22, v63
	v_add_u32_e32 v26, v96, v112
	ds_write_b32 v26, v25 offset:8704
	v_cvt_pk_bf16_f32 v25, v25, s0
	ds_write_b16 v160, v25 offset:26384
	v_fma_f32 v25, v21, v61, v24
; __device__ __forceinline__ float sigmoidf_(float x) { return __builtin_amdgcn_rcpf(1.0f + __expf(-x)); }
; template <bool FINAL>
; __device__ void phase_lru(const Params& p, int l, unsigned char* smem) {
;     ...
;     for (int d = 0; d < 2; ++d) {
;       {
;         bf16x8 uf[2];
;         uf[0] = *(const bf16x8*)(ub + (16 * w + l15) * 72 + g * 8);
;         uf[1] = *(const bf16x8*)(ub + (16 * w + l15) * 72 + 32 + g * 8);
;         const int t = 16 * w + l15;
; #pragma unroll
;         for (int et = 0; et < 4; ++et) {
;           f32x4 ar = {0.f, 0.f, 0.f, 0.f}, ai = {0.f, 0.f, 0.f, 0.f};
;           const u16* wr = p.WLRU + ((((size_t)(l * 2 + d) * 2 + 0) * 8 + nb) * 64 + et * 16 + l15) * 64 + g * 8;
;           const u16* wi = p.WLRU + ((((size_t)(l * 2 + d) * 2 + 1) * 8 + nb) * 64 + et * 16 + l15) * 64 + g * 8;
; #pragma unroll
;           for (int ks = 0; ks < 2; ++ks) {
;             ar = mfma16(*(const bf16x8*)(wr + ks * 32), uf[ks], ar);
;             ai = mfma16(*(const bf16x8*)(wi + ks * 32), uf[ks], ai);
;           }
;           const int e0 = et * 16 + 4 * g, ch0 = nb * 64 + e0;
;           const float4 ba4 = *(const float4*)(p.ba + (l * 2 + d) * 512 + ch0);
;           const float4 bx4 = *(const float4*)(p.bx + (l * 2 + d) * 512 + ch0);
;           const float4 sp4 = *(const float4*)(p.SP8 + (l * 2 + d) * 512 + ch0);
;           const float4 uu = *(const float4*)(u32 + t * 64 + e0);
;           const float* bap = (const float*)&ba4; const float* bxp = (const float*)&bx4;
;           const float* spp = (const float*)&sp4; const float* uup = (const float*)&uu;
;           f32x4 av, bv;
; #pragma unroll
;           for (int j = 0; j < 4; ++j) {
;             float r = sigmoidf_(ar[j] + bap[j]);
;             float ig = sigmoidf_(ai[j] + bxp[j]);
;             float la = spp[j] * r;
;             float av_ = __expf(la);
;             float t2 = 2.0f * la;
;             float ser = -t2 * (1.f + t2 * 0.5f * (1.f + t2 * (1.f / 3.f) * (1.f + t2 * 0.25f * (1.f + t2 * 0.2f))));
;             float om = (t2 > -0.25f) ? ser : (1.0f - av_ * av_);
;             av[j] = av_;
;             bv[j] = __builtin_amdgcn_sqrtf(om) * ig * uup[j];
;           }
;           *(f32x4*)(sa + t * 64 + e0) = av;
;           *(f32x4*)(sb + t * 64 + e0) = bv;
;         }
	v_fmac_f32_e32 v25, v20, v62
	v_fmac_f32_e32 v25, v23, v63
	v_fmac_f32_e32 v25, v22, v64
	v_add_u32_e32 v26, v96, v113
	ds_write_b32 v26, v25 offset:8704
	v_cvt_pk_bf16_f32 v25, v25, s0
	ds_write_b16 v160, v25 offset:26528
	v_fma_f32 v25, v21, v62, v24
	v_fmac_f32_e32 v25, v20, v63
	v_fmac_f32_e32 v25, v23, v64
	v_fmac_f32_e32 v25, v22, v65
	v_add_u32_e32 v26, v96, v114
	ds_write_b32 v26, v25 offset:8704
	v_cvt_pk_bf16_f32 v25, v25, s0
	ds_write_b16 v160, v25 offset:26672
	v_fma_f32 v25, v21, v63, v24
	v_fmac_f32_e32 v25, v20, v64
	v_fmac_f32_e32 v25, v23, v65
	v_fmac_f32_e32 v25, v22, v66
	v_add_u32_e32 v26, v96, v115
	ds_write_b32 v26, v25 offset:8704
	v_cvt_pk_bf16_f32 v25, v25, s0
	ds_write_b16 v160, v25 offset:26816
	v_fma_f32 v25, v21, v64, v24
	v_fmac_f32_e32 v24, v21, v65
	v_fmac_f32_e32 v24, v20, v66
	v_fmac_f32_e32 v24, v23, v67
	v_fmac_f32_e32 v25, v20, v65
	v_fmac_f32_e32 v24, v22, v68
	v_add_u32_e32 v20, v96, v117
	ds_write_b32 v20, v24 offset:8704
	v_cvt_pk_bf16_f32 v20, v24, s0
	v_fmac_f32_e32 v25, v23, v66
	ds_write_b16 v160, v20 offset:27104
	v_or_b32_e32 v20, s40, v39
	v_fmac_f32_e32 v25, v22, v67
	v_add_u32_e32 v26, v96, v116
	v_lshlrev_b32_e32 v144, 7, v20
	ds_write_b32 v26, v25 offset:8704
	v_cvt_pk_bf16_f32 v25, v25, s0
	v_lshl_add_u64 v[20:21], s[42:43], 0, v[144:145]
	v_lshlrev_b32_e32 v62, 1, v50
	v_mov_b32_e32 v63, v145
	ds_write_b16 v160, v25 offset:26960
	s_waitcnt lgkmcnt(0)
	s_barrier
	ds_write_b128 v41, v[12:15]
	ds_write_b128 v41, v[16:19] offset:4096
	s_mov_b32 s5, 0x3e4ccccd
	global_load_dwordx4 v[196:199], v231, s[58:59]
	global_load_dwordx4 v[200:203], v231, s[60:61]
	global_load_dwordx4 v[32:35], v231, s[62:63]
	ds_read_b128 v[12:15], v229 offset:25088
	ds_read_b128 v[16:19], v229 offset:25152
	ds_read_b128 v[28:31], v230 offset:8704
	s_waitcnt lgkmcnt(1)
	v_mfma_f32_16x16x32_bf16 v[20:23], v[180:183], v[12:15], 0
	v_mfma_f32_16x16x32_bf16 v[24:27], v[188:191], v[12:15], 0
	v_mfma_f32_16x16x32_bf16 v[20:23], v[184:187], v[16:19], v[20:23]
	v_mfma_f32_16x16x32_bf16 v[24:27], v[192:195], v[16:19], v[24:27]
	s_waitcnt vmcnt(0)
	s_nop 7
	s_nop 3
	s_waitcnt lgkmcnt(0)
	v_add_f32_e32 v20, v20, v196
	v_add_f32_e32 v21, v21, v197
	v_add_f32_e32 v24, v24, v200
	v_add_f32_e32 v25, v25, v201
	v_mul_f32_e32 v20, 0xbfb8aa3b, v20
	v_mul_f32_e32 v21, 0xbfb8aa3b, v21
	v_mul_f32_e32 v24, 0xbfb8aa3b, v24
	v_mul_f32_e32 v25, 0xbfb8aa3b, v25
	v_exp_f32_e32 v20, v20
	v_exp_f32_e32 v21, v21
	v_exp_f32_e32 v24, v24
	v_exp_f32_e32 v25, v25
	v_add_f32_e32 v20, 1.0, v20
	v_add_f32_e32 v21, 1.0, v21
	v_add_f32_e32 v24, 1.0, v24
	v_add_f32_e32 v25, 1.0, v25
	v_rcp_f32_e32 v20, v20
	v_rcp_f32_e32 v21, v21
	v_rcp_f32_e32 v24, v24
	v_rcp_f32_e32 v25, v25
	v_pk_mul_f32 v[12:13], v[20:21], v[32:33]
	s_nop 0
	v_pk_add_f32 v[14:15], v[12:13], v[12:13]
	v_mul_f32_e32 v20, 0x3fb8aa3b, v12
	v_mul_f32_e32 v21, 0x3fb8aa3b, v13
	v_exp_f32_e32 v20, v20
	v_exp_f32_e32 v21, v21
	v_mul_f32_e32 v16, 0x3e800000, v14
	v_fma_f32 v17, v14, s5, 1.0
	v_mul_f32_e32 v18, 0x3eaaaaab, v14
	v_fma_f32 v16, v16, v17, 1.0
	v_mul_f32_e32 v17, 0.5, v14
	v_fma_f32 v18, v18, v16, 1.0
	v_fma_f32 v17, v17, v18, 1.0
	v_mul_f32_e64 v17, v17, -v14
	v_fma_f32 v16, -v20, v20, 1.0
	v_cmp_lt_f32_e32 vcc, s6, v14
	v_mul_f32_e32 v19, 0x3e800000, v15
	v_fma_f32 v12, v15, s5, 1.0
	v_cndmask_b32_e32 v16, v16, v17, vcc
	v_mul_f32_e32 v13, 0x3eaaaaab, v15
	v_fma_f32 v19, v19, v12, 1.0
	v_mul_f32_e32 v12, 0.5, v15
	v_fma_f32 v13, v13, v19, 1.0
	v_fma_f32 v12, v12, v13, 1.0
	v_mul_f32_e64 v12, v12, -v15
	v_fma_f32 v13, -v21, v21, 1.0
	v_cmp_lt_f32_e32 vcc, s6, v15
	v_sqrt_f32_e32 v16, v16
	s_nop 1
	v_cndmask_b32_e32 v17, v13, v12, vcc
	v_sqrt_f32_e32 v17, v17
	s_nop 0
	v_pk_mul_f32 v[24:25], v[24:25], v[16:17]
	s_nop 0
	v_pk_mul_f32 v[24:25], v[28:29], v[24:25]
	v_add_f32_e32 v22, v22, v198
	v_add_f32_e32 v23, v23, v199
	v_add_f32_e32 v26, v26, v202
	v_add_f32_e32 v27, v27, v203
	v_mul_f32_e32 v22, 0xbfb8aa3b, v22
	v_mul_f32_e32 v23, 0xbfb8aa3b, v23
	v_mul_f32_e32 v26, 0xbfb8aa3b, v26
	v_mul_f32_e32 v27, 0xbfb8aa3b, v27
	v_exp_f32_e32 v22, v22
	v_exp_f32_e32 v23, v23
	v_exp_f32_e32 v26, v26
	v_exp_f32_e32 v27, v27
	v_add_f32_e32 v22, 1.0, v22
	v_add_f32_e32 v23, 1.0, v23
	v_add_f32_e32 v26, 1.0, v26
	v_add_f32_e32 v27, 1.0, v27
	v_rcp_f32_e32 v22, v22
	v_rcp_f32_e32 v23, v23
	v_rcp_f32_e32 v26, v26
	v_rcp_f32_e32 v27, v27
	v_pk_mul_f32 v[12:13], v[22:23], v[34:35]
	s_nop 0
	v_pk_add_f32 v[14:15], v[12:13], v[12:13]
	v_mul_f32_e32 v22, 0x3fb8aa3b, v12
	v_mul_f32_e32 v23, 0x3fb8aa3b, v13
	v_exp_f32_e32 v22, v22
	v_exp_f32_e32 v23, v23
	v_mul_f32_e32 v16, 0x3e800000, v14
	v_fma_f32 v17, v14, s5, 1.0
	v_mul_f32_e32 v18, 0x3eaaaaab, v14
	v_fma_f32 v16, v16, v17, 1.0
	v_mul_f32_e32 v17, 0.5, v14
	v_fma_f32 v18, v18, v16, 1.0
	v_fma_f32 v17, v17, v18, 1.0
	v_mul_f32_e64 v17, v17, -v14
	v_fma_f32 v16, -v22, v22, 1.0
	v_cmp_lt_f32_e32 vcc, s6, v14
	v_mul_f32_e32 v19, 0x3e800000, v15
	v_fma_f32 v12, v15, s5, 1.0
	v_cndmask_b32_e32 v16, v16, v17, vcc
	v_mul_f32_e32 v13, 0x3eaaaaab, v15
	v_fma_f32 v19, v19, v12, 1.0
	v_mul_f32_e32 v12, 0.5, v15
	v_fma_f32 v13, v13, v19, 1.0
	v_fma_f32 v12, v12, v13, 1.0
	v_mul_f32_e64 v12, v12, -v15
	v_fma_f32 v13, -v23, v23, 1.0
	v_cmp_lt_f32_e32 vcc, s6, v15
	v_sqrt_f32_e32 v16, v16
	s_nop 1
	v_cndmask_b32_e32 v17, v13, v12, vcc
	v_sqrt_f32_e32 v17, v17
	s_nop 0
	v_pk_mul_f32 v[26:27], v[26:27], v[16:17]
	s_nop 0
	v_pk_mul_f32 v[26:27], v[30:31], v[26:27]
	ds_write_b128 v230, v[20:23] offset:34304
	ds_write_b128 v230, v[24:27] offset:50688
	ds_read_b128 v[12:15], v229 offset:27392
	ds_read_b128 v[16:19], v229 offset:27456
	ds_read_b128 v[28:31], v230 offset:12800
	s_waitcnt lgkmcnt(1)
; __device__ __forceinline__ float sigmoidf_(float x) { return __builtin_amdgcn_rcpf(1.0f + __expf(-x)); }
; template <bool FINAL>
; __device__ void phase_lru(const Params& p, int l, unsigned char* smem) {
;     ...
; #pragma unroll
;         for (int et = 0; et < 4; ++et) {
;           f32x4 ar = {0.f, 0.f, 0.f, 0.f}, ai = {0.f, 0.f, 0.f, 0.f};
;           const u16* wr = p.WLRU + ((((size_t)(l * 2 + d) * 2 + 0) * 8 + nb) * 64 + et * 16 + l15) * 64 + g * 8;
;           const u16* wi = p.WLRU + ((((size_t)(l * 2 + d) * 2 + 1) * 8 + nb) * 64 + et * 16 + l15) * 64 + g * 8;
; #pragma unroll
;           for (int ks = 0; ks < 2; ++ks) {
;             ar = mfma16(*(const bf16x8*)(wr + ks * 32), uf[ks], ar);
;             ai = mfma16(*(const bf16x8*)(wi + ks * 32), uf[ks], ai);
;           }
;           const int e0 = et * 16 + 4 * g, ch0 = nb * 64 + e0;
;           const float4 ba4 = *(const float4*)(p.ba + (l * 2 + d) * 512 + ch0);
;           const float4 bx4 = *(const float4*)(p.bx + (l * 2 + d) * 512 + ch0);
;           const float4 sp4 = *(const float4*)(p.SP8 + (l * 2 + d) * 512 + ch0);
;           const float4 uu = *(const float4*)(u32 + t * 64 + e0);
;           const float* bap = (const float*)&ba4; const float* bxp = (const float*)&bx4;
;           const float* spp = (const float*)&sp4; const float* uup = (const float*)&uu;
;           f32x4 av, bv;
; #pragma unroll
;           for (int j = 0; j < 4; ++j) {
;             float r = sigmoidf_(ar[j] + bap[j]);
;             float ig = sigmoidf_(ai[j] + bxp[j]);
;             float la = spp[j] * r;
;             float av_ = __expf(la);
;             float t2 = 2.0f * la;
;             float ser = -t2 * (1.f + t2 * 0.5f * (1.f + t2 * (1.f / 3.f) * (1.f + t2 * 0.25f * (1.f + t2 * 0.2f))));
;             float om = (t2 > -0.25f) ? ser : (1.0f - av_ * av_);
;             av[j] = av_;
;             bv[j] = __builtin_amdgcn_sqrtf(om) * ig * uup[j];
;           }
;           *(f32x4*)(sa + t * 64 + e0) = av;
;           *(f32x4*)(sb + t * 64 + e0) = bv;
	v_mfma_f32_16x16x32_bf16 v[20:23], v[180:183], v[12:15], 0
	v_mfma_f32_16x16x32_bf16 v[24:27], v[188:191], v[12:15], 0
	v_mfma_f32_16x16x32_bf16 v[20:23], v[184:187], v[16:19], v[20:23]
	v_mfma_f32_16x16x32_bf16 v[24:27], v[192:195], v[16:19], v[24:27]
	s_nop 7
	s_nop 3
	s_waitcnt lgkmcnt(0)
	v_add_f32_e32 v20, v20, v196
	v_add_f32_e32 v21, v21, v197
	v_add_f32_e32 v24, v24, v200
	v_add_f32_e32 v25, v25, v201
	v_mul_f32_e32 v20, 0xbfb8aa3b, v20
	v_mul_f32_e32 v21, 0xbfb8aa3b, v21
	v_mul_f32_e32 v24, 0xbfb8aa3b, v24
	v_mul_f32_e32 v25, 0xbfb8aa3b, v25
	v_exp_f32_e32 v20, v20
	v_exp_f32_e32 v21, v21
	v_exp_f32_e32 v24, v24
	v_exp_f32_e32 v25, v25
	v_add_f32_e32 v20, 1.0, v20
	v_add_f32_e32 v21, 1.0, v21
	v_add_f32_e32 v24, 1.0, v24
	v_add_f32_e32 v25, 1.0, v25
	v_rcp_f32_e32 v20, v20
	v_rcp_f32_e32 v21, v21
	v_rcp_f32_e32 v24, v24
	v_rcp_f32_e32 v25, v25
	v_pk_mul_f32 v[12:13], v[20:21], v[32:33]
	s_nop 0
	v_pk_add_f32 v[14:15], v[12:13], v[12:13]
	v_mul_f32_e32 v20, 0x3fb8aa3b, v12
	v_mul_f32_e32 v21, 0x3fb8aa3b, v13
	v_exp_f32_e32 v20, v20
	v_exp_f32_e32 v21, v21
	v_mul_f32_e32 v16, 0x3e800000, v14
	v_fma_f32 v17, v14, s5, 1.0
	v_mul_f32_e32 v18, 0x3eaaaaab, v14
	v_fma_f32 v16, v16, v17, 1.0
	v_mul_f32_e32 v17, 0.5, v14
	v_fma_f32 v18, v18, v16, 1.0
	v_fma_f32 v17, v17, v18, 1.0
	v_mul_f32_e64 v17, v17, -v14
	v_fma_f32 v16, -v20, v20, 1.0
	v_cmp_lt_f32_e32 vcc, s6, v14
	v_mul_f32_e32 v19, 0x3e800000, v15
	v_fma_f32 v12, v15, s5, 1.0
	v_cndmask_b32_e32 v16, v16, v17, vcc
	v_mul_f32_e32 v13, 0x3eaaaaab, v15
	v_fma_f32 v19, v19, v12, 1.0
	v_mul_f32_e32 v12, 0.5, v15
	v_fma_f32 v13, v13, v19, 1.0
	v_fma_f32 v12, v12, v13, 1.0
	v_mul_f32_e64 v12, v12, -v15
	v_fma_f32 v13, -v21, v21, 1.0
	v_cmp_lt_f32_e32 vcc, s6, v15
	v_sqrt_f32_e32 v16, v16
	s_nop 1
	v_cndmask_b32_e32 v17, v13, v12, vcc
	v_sqrt_f32_e32 v17, v17
	s_nop 0
	v_pk_mul_f32 v[24:25], v[24:25], v[16:17]
	s_nop 0
	v_pk_mul_f32 v[24:25], v[28:29], v[24:25]
	v_add_f32_e32 v22, v22, v198
	v_add_f32_e32 v23, v23, v199
	v_add_f32_e32 v26, v26, v202
	v_add_f32_e32 v27, v27, v203
	v_mul_f32_e32 v22, 0xbfb8aa3b, v22
	v_mul_f32_e32 v23, 0xbfb8aa3b, v23
	v_mul_f32_e32 v26, 0xbfb8aa3b, v26
	v_mul_f32_e32 v27, 0xbfb8aa3b, v27
	v_exp_f32_e32 v22, v22
	v_exp_f32_e32 v23, v23
	v_exp_f32_e32 v26, v26
	v_exp_f32_e32 v27, v27
	v_add_f32_e32 v22, 1.0, v22
	v_add_f32_e32 v23, 1.0, v23
	v_add_f32_e32 v26, 1.0, v26
	v_add_f32_e32 v27, 1.0, v27
	v_rcp_f32_e32 v22, v22
	v_rcp_f32_e32 v23, v23
	v_rcp_f32_e32 v26, v26
	v_rcp_f32_e32 v27, v27
	v_pk_mul_f32 v[12:13], v[22:23], v[34:35]
	s_nop 0
	v_pk_add_f32 v[14:15], v[12:13], v[12:13]
	v_mul_f32_e32 v22, 0x3fb8aa3b, v12
	v_mul_f32_e32 v23, 0x3fb8aa3b, v13
	v_exp_f32_e32 v22, v22
	v_exp_f32_e32 v23, v23
	v_mul_f32_e32 v16, 0x3e800000, v14
	v_fma_f32 v17, v14, s5, 1.0
	v_mul_f32_e32 v18, 0x3eaaaaab, v14
	v_fma_f32 v16, v16, v17, 1.0
	v_mul_f32_e32 v17, 0.5, v14
	v_fma_f32 v18, v18, v16, 1.0
	v_fma_f32 v17, v17, v18, 1.0
	v_mul_f32_e64 v17, v17, -v14
	v_fma_f32 v16, -v22, v22, 1.0
	v_cmp_lt_f32_e32 vcc, s6, v14
	v_mul_f32_e32 v19, 0x3e800000, v15
	v_fma_f32 v12, v15, s5, 1.0
	v_cndmask_b32_e32 v16, v16, v17, vcc
	v_mul_f32_e32 v13, 0x3eaaaaab, v15
	v_fma_f32 v19, v19, v12, 1.0
	v_mul_f32_e32 v12, 0.5, v15
	v_fma_f32 v13, v13, v19, 1.0
	v_fma_f32 v12, v12, v13, 1.0
	v_mul_f32_e64 v12, v12, -v15
	v_fma_f32 v13, -v23, v23, 1.0
	v_cmp_lt_f32_e32 vcc, s6, v15
	v_sqrt_f32_e32 v16, v16
	s_nop 1
	v_cndmask_b32_e32 v17, v13, v12, vcc
	v_sqrt_f32_e32 v17, v17
	s_nop 0
	v_pk_mul_f32 v[26:27], v[26:27], v[16:17]
	s_nop 0
	v_pk_mul_f32 v[26:27], v[30:31], v[26:27]
	ds_write_b128 v230, v[20:23] offset:38400
	ds_write_b128 v230, v[24:27] offset:54784
	ds_read_b128 v[12:15], v229 offset:29696
	ds_read_b128 v[16:19], v229 offset:29760
	ds_read_b128 v[28:31], v230 offset:16896
	s_waitcnt lgkmcnt(1)
	v_mfma_f32_16x16x32_bf16 v[20:23], v[180:183], v[12:15], 0
	v_mfma_f32_16x16x32_bf16 v[24:27], v[188:191], v[12:15], 0
	v_mfma_f32_16x16x32_bf16 v[20:23], v[184:187], v[16:19], v[20:23]
	v_mfma_f32_16x16x32_bf16 v[24:27], v[192:195], v[16:19], v[24:27]
	s_nop 7
	s_nop 3
	s_waitcnt lgkmcnt(0)
	v_add_f32_e32 v20, v20, v196
	v_add_f32_e32 v21, v21, v197
	v_add_f32_e32 v24, v24, v200
	v_add_f32_e32 v25, v25, v201
	v_mul_f32_e32 v20, 0xbfb8aa3b, v20
	v_mul_f32_e32 v21, 0xbfb8aa3b, v21
	v_mul_f32_e32 v24, 0xbfb8aa3b, v24
	v_mul_f32_e32 v25, 0xbfb8aa3b, v25
	v_exp_f32_e32 v20, v20
	v_exp_f32_e32 v21, v21
	v_exp_f32_e32 v24, v24
	v_exp_f32_e32 v25, v25
	v_add_f32_e32 v20, 1.0, v20
	v_add_f32_e32 v21, 1.0, v21
	v_add_f32_e32 v24, 1.0, v24
	v_add_f32_e32 v25, 1.0, v25
	v_rcp_f32_e32 v20, v20
	v_rcp_f32_e32 v21, v21
	v_rcp_f32_e32 v24, v24
	v_rcp_f32_e32 v25, v25
	v_pk_mul_f32 v[12:13], v[20:21], v[32:33]
	s_nop 0
	v_pk_add_f32 v[14:15], v[12:13], v[12:13]
	v_mul_f32_e32 v20, 0x3fb8aa3b, v12
	v_mul_f32_e32 v21, 0x3fb8aa3b, v13
	v_exp_f32_e32 v20, v20
	v_exp_f32_e32 v21, v21
	v_mul_f32_e32 v16, 0x3e800000, v14
	v_fma_f32 v17, v14, s5, 1.0
	v_mul_f32_e32 v18, 0x3eaaaaab, v14
	v_fma_f32 v16, v16, v17, 1.0
	v_mul_f32_e32 v17, 0.5, v14
	v_fma_f32 v18, v18, v16, 1.0
	v_fma_f32 v17, v17, v18, 1.0
	v_mul_f32_e64 v17, v17, -v14
	v_fma_f32 v16, -v20, v20, 1.0
	v_cmp_lt_f32_e32 vcc, s6, v14
	v_mul_f32_e32 v19, 0x3e800000, v15
	v_fma_f32 v12, v15, s5, 1.0
	v_cndmask_b32_e32 v16, v16, v17, vcc
	v_mul_f32_e32 v13, 0x3eaaaaab, v15
	v_fma_f32 v19, v19, v12, 1.0
	v_mul_f32_e32 v12, 0.5, v15
	v_fma_f32 v13, v13, v19, 1.0
	v_fma_f32 v12, v12, v13, 1.0
	v_mul_f32_e64 v12, v12, -v15
	v_fma_f32 v13, -v21, v21, 1.0
	v_cmp_lt_f32_e32 vcc, s6, v15
	v_sqrt_f32_e32 v16, v16
	s_nop 1
	v_cndmask_b32_e32 v17, v13, v12, vcc
; __device__ __forceinline__ float sigmoidf_(float x) { return __builtin_amdgcn_rcpf(1.0f + __expf(-x)); }
; template <bool FINAL>
; __device__ void phase_lru(const Params& p, int l, unsigned char* smem) {
;     ...
;       {
;         bf16x8 uf[2];
;         uf[0] = *(const bf16x8*)(ub + (16 * w + l15) * 72 + g * 8);
;         uf[1] = *(const bf16x8*)(ub + (16 * w + l15) * 72 + 32 + g * 8);
;         const int t = 16 * w + l15;
; #pragma unroll
;         for (int et = 0; et < 4; ++et) {
;           f32x4 ar = {0.f, 0.f, 0.f, 0.f}, ai = {0.f, 0.f, 0.f, 0.f};
;           const u16* wr = p.WLRU + ((((size_t)(l * 2 + d) * 2 + 0) * 8 + nb) * 64 + et * 16 + l15) * 64 + g * 8;
;           const u16* wi = p.WLRU + ((((size_t)(l * 2 + d) * 2 + 1) * 8 + nb) * 64 + et * 16 + l15) * 64 + g * 8;
; #pragma unroll
;           for (int ks = 0; ks < 2; ++ks) {
;             ar = mfma16(*(const bf16x8*)(wr + ks * 32), uf[ks], ar);
;             ai = mfma16(*(const bf16x8*)(wi + ks * 32), uf[ks], ai);
;           }
;           const int e0 = et * 16 + 4 * g, ch0 = nb * 64 + e0;
;           const float4 ba4 = *(const float4*)(p.ba + (l * 2 + d) * 512 + ch0);
;           const float4 bx4 = *(const float4*)(p.bx + (l * 2 + d) * 512 + ch0);
;           const float4 sp4 = *(const float4*)(p.SP8 + (l * 2 + d) * 512 + ch0);
;           const float4 uu = *(const float4*)(u32 + t * 64 + e0);
;           const float* bap = (const float*)&ba4; const float* bxp = (const float*)&bx4;
;           const float* spp = (const float*)&sp4; const float* uup = (const float*)&uu;
;           f32x4 av, bv;
; #pragma unroll
;           for (int j = 0; j < 4; ++j) {
;             float r = sigmoidf_(ar[j] + bap[j]);
;             float ig = sigmoidf_(ai[j] + bxp[j]);
;             float la = spp[j] * r;
;             float av_ = __expf(la);
;             float t2 = 2.0f * la;
;             float ser = -t2 * (1.f + t2 * 0.5f * (1.f + t2 * (1.f / 3.f) * (1.f + t2 * 0.25f * (1.f + t2 * 0.2f))));
;             float om = (t2 > -0.25f) ? ser : (1.0f - av_ * av_);
;             av[j] = av_;
;             bv[j] = __builtin_amdgcn_sqrtf(om) * ig * uup[j];
;           }
;           *(f32x4*)(sa + t * 64 + e0) = av;
;           *(f32x4*)(sb + t * 64 + e0) = bv;
;         }
;       }
;       __syncthreads();
	v_sqrt_f32_e32 v17, v17
	s_nop 0
	v_pk_mul_f32 v[24:25], v[24:25], v[16:17]
	s_nop 0
	v_pk_mul_f32 v[24:25], v[28:29], v[24:25]
	v_add_f32_e32 v22, v22, v198
	v_add_f32_e32 v23, v23, v199
	v_add_f32_e32 v26, v26, v202
	v_add_f32_e32 v27, v27, v203
	v_mul_f32_e32 v22, 0xbfb8aa3b, v22
	v_mul_f32_e32 v23, 0xbfb8aa3b, v23
	v_mul_f32_e32 v26, 0xbfb8aa3b, v26
	v_mul_f32_e32 v27, 0xbfb8aa3b, v27
	v_exp_f32_e32 v22, v22
	v_exp_f32_e32 v23, v23
	v_exp_f32_e32 v26, v26
	v_exp_f32_e32 v27, v27
	v_add_f32_e32 v22, 1.0, v22
	v_add_f32_e32 v23, 1.0, v23
	v_add_f32_e32 v26, 1.0, v26
	v_add_f32_e32 v27, 1.0, v27
	v_rcp_f32_e32 v22, v22
	v_rcp_f32_e32 v23, v23
	v_rcp_f32_e32 v26, v26
	v_rcp_f32_e32 v27, v27
	v_pk_mul_f32 v[12:13], v[22:23], v[34:35]
	s_nop 0
	v_pk_add_f32 v[14:15], v[12:13], v[12:13]
	v_mul_f32_e32 v22, 0x3fb8aa3b, v12
	v_mul_f32_e32 v23, 0x3fb8aa3b, v13
	v_exp_f32_e32 v22, v22
	v_exp_f32_e32 v23, v23
	v_mul_f32_e32 v16, 0x3e800000, v14
	v_fma_f32 v17, v14, s5, 1.0
	v_mul_f32_e32 v18, 0x3eaaaaab, v14
	v_fma_f32 v16, v16, v17, 1.0
	v_mul_f32_e32 v17, 0.5, v14
	v_fma_f32 v18, v18, v16, 1.0
	v_fma_f32 v17, v17, v18, 1.0
	v_mul_f32_e64 v17, v17, -v14
	v_fma_f32 v16, -v22, v22, 1.0
	v_cmp_lt_f32_e32 vcc, s6, v14
	v_mul_f32_e32 v19, 0x3e800000, v15
	v_fma_f32 v12, v15, s5, 1.0
	v_cndmask_b32_e32 v16, v16, v17, vcc
	v_mul_f32_e32 v13, 0x3eaaaaab, v15
	v_fma_f32 v19, v19, v12, 1.0
	v_mul_f32_e32 v12, 0.5, v15
	v_fma_f32 v13, v13, v19, 1.0
	v_fma_f32 v12, v12, v13, 1.0
	v_mul_f32_e64 v12, v12, -v15
	v_fma_f32 v13, -v23, v23, 1.0
	v_cmp_lt_f32_e32 vcc, s6, v15
	v_sqrt_f32_e32 v16, v16
	s_nop 1
	v_cndmask_b32_e32 v17, v13, v12, vcc
	v_sqrt_f32_e32 v17, v17
	s_nop 0
	v_pk_mul_f32 v[26:27], v[26:27], v[16:17]
	s_nop 0
	v_pk_mul_f32 v[26:27], v[30:31], v[26:27]
	ds_write_b128 v230, v[20:23] offset:42496
	ds_write_b128 v230, v[24:27] offset:58880
	ds_read_b128 v[12:15], v229 offset:32000
	ds_read_b128 v[16:19], v229 offset:32064
	ds_read_b128 v[28:31], v230 offset:20992
	s_waitcnt lgkmcnt(1)
	v_mfma_f32_16x16x32_bf16 v[20:23], v[180:183], v[12:15], 0
	v_mfma_f32_16x16x32_bf16 v[24:27], v[188:191], v[12:15], 0
	v_mfma_f32_16x16x32_bf16 v[20:23], v[184:187], v[16:19], v[20:23]
	v_mfma_f32_16x16x32_bf16 v[24:27], v[192:195], v[16:19], v[24:27]
	s_nop 7
	s_nop 3
	s_waitcnt lgkmcnt(0)
	v_add_f32_e32 v20, v20, v196
	v_add_f32_e32 v21, v21, v197
	v_add_f32_e32 v24, v24, v200
	v_add_f32_e32 v25, v25, v201
	v_mul_f32_e32 v20, 0xbfb8aa3b, v20
	v_mul_f32_e32 v21, 0xbfb8aa3b, v21
	v_mul_f32_e32 v24, 0xbfb8aa3b, v24
	v_mul_f32_e32 v25, 0xbfb8aa3b, v25
	v_exp_f32_e32 v20, v20
	v_exp_f32_e32 v21, v21
	v_exp_f32_e32 v24, v24
	v_exp_f32_e32 v25, v25
	v_add_f32_e32 v20, 1.0, v20
	v_add_f32_e32 v21, 1.0, v21
	v_add_f32_e32 v24, 1.0, v24
	v_add_f32_e32 v25, 1.0, v25
	v_rcp_f32_e32 v20, v20
	v_rcp_f32_e32 v21, v21
	v_rcp_f32_e32 v24, v24
	v_rcp_f32_e32 v25, v25
	v_pk_mul_f32 v[12:13], v[20:21], v[32:33]
	s_nop 0
	v_pk_add_f32 v[14:15], v[12:13], v[12:13]
	v_mul_f32_e32 v20, 0x3fb8aa3b, v12
	v_mul_f32_e32 v21, 0x3fb8aa3b, v13
	v_exp_f32_e32 v20, v20
	v_exp_f32_e32 v21, v21
	v_mul_f32_e32 v16, 0x3e800000, v14
	v_fma_f32 v17, v14, s5, 1.0
	v_mul_f32_e32 v18, 0x3eaaaaab, v14
	v_fma_f32 v16, v16, v17, 1.0
	v_mul_f32_e32 v17, 0.5, v14
	v_fma_f32 v18, v18, v16, 1.0
	v_fma_f32 v17, v17, v18, 1.0
	v_mul_f32_e64 v17, v17, -v14
	v_fma_f32 v16, -v20, v20, 1.0
	v_cmp_lt_f32_e32 vcc, s6, v14
	v_mul_f32_e32 v19, 0x3e800000, v15
	v_fma_f32 v12, v15, s5, 1.0
	v_cndmask_b32_e32 v16, v16, v17, vcc
	v_mul_f32_e32 v13, 0x3eaaaaab, v15
	v_fma_f32 v19, v19, v12, 1.0
	v_mul_f32_e32 v12, 0.5, v15
	v_fma_f32 v13, v13, v19, 1.0
	v_fma_f32 v12, v12, v13, 1.0
	v_mul_f32_e64 v12, v12, -v15
	v_fma_f32 v13, -v21, v21, 1.0
	v_cmp_lt_f32_e32 vcc, s6, v15
	v_sqrt_f32_e32 v16, v16
	s_nop 1
	v_cndmask_b32_e32 v17, v13, v12, vcc
	v_sqrt_f32_e32 v17, v17
	s_nop 0
	v_pk_mul_f32 v[24:25], v[24:25], v[16:17]
	s_nop 0
	v_pk_mul_f32 v[24:25], v[28:29], v[24:25]
	v_add_f32_e32 v22, v22, v198
	v_add_f32_e32 v23, v23, v199
	v_add_f32_e32 v26, v26, v202
	v_add_f32_e32 v27, v27, v203
	v_mul_f32_e32 v22, 0xbfb8aa3b, v22
	v_mul_f32_e32 v23, 0xbfb8aa3b, v23
	v_mul_f32_e32 v26, 0xbfb8aa3b, v26
	v_mul_f32_e32 v27, 0xbfb8aa3b, v27
	v_exp_f32_e32 v22, v22
	v_exp_f32_e32 v23, v23
	v_exp_f32_e32 v26, v26
	v_exp_f32_e32 v27, v27
	v_add_f32_e32 v22, 1.0, v22
	v_add_f32_e32 v23, 1.0, v23
	v_add_f32_e32 v26, 1.0, v26
	v_add_f32_e32 v27, 1.0, v27
	v_rcp_f32_e32 v22, v22
	v_rcp_f32_e32 v23, v23
	v_rcp_f32_e32 v26, v26
	v_rcp_f32_e32 v27, v27
	v_pk_mul_f32 v[12:13], v[22:23], v[34:35]
	s_nop 0
	v_pk_add_f32 v[14:15], v[12:13], v[12:13]
	v_mul_f32_e32 v22, 0x3fb8aa3b, v12
	v_mul_f32_e32 v23, 0x3fb8aa3b, v13
	v_exp_f32_e32 v22, v22
	v_exp_f32_e32 v23, v23
	v_mul_f32_e32 v16, 0x3e800000, v14
	v_fma_f32 v17, v14, s5, 1.0
	v_mul_f32_e32 v18, 0x3eaaaaab, v14
	v_fma_f32 v16, v16, v17, 1.0
	v_mul_f32_e32 v17, 0.5, v14
	v_fma_f32 v18, v18, v16, 1.0
	v_fma_f32 v17, v17, v18, 1.0
	v_mul_f32_e64 v17, v17, -v14
	v_fma_f32 v16, -v22, v22, 1.0
	v_cmp_lt_f32_e32 vcc, s6, v14
	v_mul_f32_e32 v19, 0x3e800000, v15
	v_fma_f32 v12, v15, s5, 1.0
	v_cndmask_b32_e32 v16, v16, v17, vcc
	v_mul_f32_e32 v13, 0x3eaaaaab, v15
	v_fma_f32 v19, v19, v12, 1.0
	v_mul_f32_e32 v12, 0.5, v15
	v_fma_f32 v13, v13, v19, 1.0
	v_fma_f32 v12, v12, v13, 1.0
	v_mul_f32_e64 v12, v12, -v15
	v_fma_f32 v13, -v23, v23, 1.0
	v_cmp_lt_f32_e32 vcc, s6, v15
	v_sqrt_f32_e32 v16, v16
	s_nop 1
	v_cndmask_b32_e32 v17, v13, v12, vcc
	v_sqrt_f32_e32 v17, v17
	s_nop 0
	v_pk_mul_f32 v[26:27], v[26:27], v[16:17]
	s_nop 0
	v_pk_mul_f32 v[26:27], v[30:31], v[26:27]
	ds_write_b128 v230, v[20:23] offset:46592
	ds_write_b128 v230, v[24:27] offset:62976
	s_waitcnt lgkmcnt(0)
	s_barrier
; template <bool FINAL>
; __device__ void phase_lru(const Params& p, int l, unsigned char* smem) {
;     ...
;       {
;         float A = 1.f, B = 0.f;
;         if (d == 0) {
; #pragma unroll
;           for (int tt = 0; tt < 16; ++tt) { int t = qd * 16 + tt; float a = sa[t * 64 + e_], b = sb[t * 64 + e_]; B = a * B + b; A *= a; }
;         } else {
; #pragma unroll
;     ...
;         }
;         part[(0 * 4 + qd) * 64 + e_] = A;
;         part[(1 * 4 + qd) * 64 + e_] = B;
;       }
;       __syncthreads();
	ds_read2st64_b32 v[12:13], v59 offset0:134 offset1:198
	ds_read2st64_b32 v[14:15], v118 offset0:134 offset1:198
	ds_read2st64_b32 v[16:17], v119 offset0:134 offset1:198
	ds_read2st64_b32 v[64:65], v129 offset0:134 offset1:198
	ds_read2st64_b32 v[66:67], v130 offset0:134 offset1:198
	s_waitcnt lgkmcnt(4)
	v_fmac_f32_e32 v13, 0, v12
	s_waitcnt lgkmcnt(3)
	v_mul_f32_e32 v18, v12, v14
	s_waitcnt lgkmcnt(2)
	v_mul_f32_e32 v20, v18, v16
	ds_read2st64_b32 v[18:19], v120 offset0:134 offset1:198
	v_fmac_f32_e32 v15, v14, v13
	v_fmac_f32_e32 v17, v16, v15
	ds_read2st64_b32 v[68:69], v131 offset0:134 offset1:198
	ds_read2st64_b32 v[70:71], v132 offset0:134 offset1:198
	s_waitcnt lgkmcnt(2)
	v_mul_f32_e32 v22, v20, v18
	ds_read2st64_b32 v[20:21], v121 offset0:134 offset1:198
	v_fmac_f32_e32 v19, v18, v17
	s_waitcnt lgkmcnt(0)
	v_mul_f32_e32 v24, v22, v20
	ds_read2st64_b32 v[22:23], v122 offset0:134 offset1:198
	v_fmac_f32_e32 v21, v20, v19
	s_waitcnt lgkmcnt(0)
	v_mul_f32_e32 v26, v24, v22
	ds_read2st64_b32 v[24:25], v123 offset0:134 offset1:198
	v_fmac_f32_e32 v23, v22, v21
	s_waitcnt lgkmcnt(0)
	v_mul_f32_e32 v28, v26, v24
	ds_read2st64_b32 v[26:27], v124 offset0:134 offset1:198
	v_fmac_f32_e32 v25, v24, v23
	s_waitcnt lgkmcnt(0)
	v_mul_f32_e32 v30, v28, v26
	ds_read2st64_b32 v[28:29], v125 offset0:134 offset1:198
	v_fmac_f32_e32 v27, v26, v25
	s_waitcnt lgkmcnt(0)
	v_mul_f32_e32 v32, v30, v28
	ds_read2st64_b32 v[30:31], v126 offset0:134 offset1:198
	v_fmac_f32_e32 v29, v28, v27
	s_waitcnt lgkmcnt(0)
	v_mul_f32_e32 v34, v32, v30
	ds_read2st64_b32 v[32:33], v127 offset0:134 offset1:198
	v_fmac_f32_e32 v31, v30, v29
	s_waitcnt lgkmcnt(0)
	v_mul_f32_e32 v63, v34, v32
	ds_read2st64_b32 v[34:35], v128 offset0:134 offset1:198
	v_fmac_f32_e32 v33, v32, v31
	s_waitcnt lgkmcnt(0)
	v_mul_f32_e32 v63, v63, v34
	v_mul_f32_e32 v63, v63, v64
	v_fmac_f32_e32 v35, v34, v33
	v_mul_f32_e32 v63, v63, v66
	v_fmac_f32_e32 v65, v64, v35
	v_mul_f32_e32 v63, v63, v68
	v_fmac_f32_e32 v67, v66, v65
	v_mul_f32_e32 v63, v63, v70
	v_fmac_f32_e32 v69, v68, v67
	v_fmac_f32_e32 v71, v70, v69
	ds_write_b32 v98, v63
	ds_write_b32 v100, v71 offset:1024
	s_waitcnt lgkmcnt(0)
	s_barrier
	s_and_saveexec_b64 s[56:57], s[22:23]
	s_cbranch_execnz .LBB0_218
	s_or_b64 exec, exec, s[56:57]
	s_and_saveexec_b64 s[56:57], s[24:25]
	s_cbranch_execnz .LBB0_219

; template <bool FINAL>
; __device__ void phase_lru(const Params& p, int l, unsigned char* smem) {
;     ...
;       {
;         bf16x8 uf[2];
;         uf[0] = *(const bf16x8*)(ub + (16 * w + l15) * 72 + g * 8);
;         uf[1] = *(const bf16x8*)(ub + (16 * w + l15) * 72 + 32 + g * 8);
;         const int t = 16 * w + l15;
; #pragma unroll
;         for (int et = 0; et < 4; ++et) {
;           f32x4 ar = {0.f, 0.f, 0.f, 0.f}, ai = {0.f, 0.f, 0.f, 0.f};
;           const u16* wr = p.WLRU + ((((size_t)(l * 2 + d) * 2 + 0) * 8 + nb) * 64 + et * 16 + l15) * 64 + g * 8;
;           const u16* wi = p.WLRU + ((((size_t)(l * 2 + d) * 2 + 1) * 8 + nb) * 64 + et * 16 + l15) * 64 + g * 8;
; #pragma unroll
;           for (int ks = 0; ks < 2; ++ks) {
;             ar = mfma16(*(const bf16x8*)(wr + ks * 32), uf[ks], ar);
;             ai = mfma16(*(const bf16x8*)(wi + ks * 32), uf[ks], ai);
;           }
;           const int e0 = et * 16 + 4 * g, ch0 = nb * 64 + e0;
;           const float4 ba4 = *(const float4*)(p.ba + (l * 2 + d) * 512 + ch0);
;           const float4 bx4 = *(const float4*)(p.bx + (l * 2 + d) * 512 + ch0);
;           const float4 sp4 = *(const float4*)(p.SP8 + (l * 2 + d) * 512 + ch0);
;           const float4 uu = *(const float4*)(u32 + t * 64 + e0);
;           const float* bap = (const float*)&ba4; const float* bxp = (const float*)&bx4;
;           const float* spp = (const float*)&sp4; const float* uup = (const float*)&uu;
;           f32x4 av, bv;
; #pragma unroll
;           for (int j = 0; j < 4; ++j) {
;             float r = sigmoidf_(ar[j] + bap[j]);
;             float ig = sigmoidf_(ai[j] + bxp[j]);
;             float la = spp[j] * r;
;             float av_ = __expf(la);
;             float t2 = 2.0f * la;
;             float ser = -t2 * (1.f + t2 * 0.5f * (1.f + t2 * (1.f / 3.f) * (1.f + t2 * 0.25f * (1.f + t2 * 0.2f))));
;             float om = (t2 > -0.25f) ? ser : (1.0f - av_ * av_);
;             av[j] = av_;
;             bv[j] = __builtin_amdgcn_sqrtf(om) * ig * uup[j];
;           }
;     ...
;           for (int tt = 0; tt < 16; ++tt) { int t = qd * 16 + tt; h = sa[t * 64 + e_] * h + sb[t * 64 + e_]; hsum[tt] += h; }
;         } else {
; #pragma unroll
;           for (int q = 3; q >= 0; --q) if (q > qd) h = part[q * 64 + e_] * h + part[(4 + q) * 64 + e_];
; #pragma unroll
;     ...
;         }
;       }
;       __syncthreads();
.LBB0_214:
	s_or_b64 exec, exec, s[56:57]
	v_lshl_add_u64 v[20:21], s[64:65], 0, v[144:145]
	v_mov_b32_e32 v63, v145
	v_lshl_add_u64 v[28:29], v[20:21], 0, v[62:63]
	ds_read2st64_b32 v[94:95], v59 offset0:134 offset1:198
	ds_read2st64_b32 v[92:93], v118 offset0:134 offset1:198
	ds_read2st64_b32 v[90:91], v119 offset0:134 offset1:198
	ds_read2st64_b32 v[88:89], v120 offset0:134 offset1:198
	ds_read2st64_b32 v[86:87], v121 offset0:134 offset1:198
	ds_read2st64_b32 v[84:85], v122 offset0:134 offset1:198
	ds_read2st64_b32 v[82:83], v123 offset0:134 offset1:198
	ds_read2st64_b32 v[80:81], v124 offset0:134 offset1:198
	ds_read2st64_b32 v[78:79], v125 offset0:134 offset1:198
	ds_read2st64_b32 v[76:77], v126 offset0:134 offset1:198
	ds_read2st64_b32 v[74:75], v127 offset0:134 offset1:198
	ds_read2st64_b32 v[72:73], v128 offset0:134 offset1:198
	ds_read2st64_b32 v[70:71], v129 offset0:134 offset1:198
	ds_read2st64_b32 v[68:69], v130 offset0:134 offset1:198
	ds_read2st64_b32 v[64:65], v131 offset0:134 offset1:198
	ds_read2st64_b32 v[66:67], v132 offset0:134 offset1:198
	s_waitcnt lgkmcnt(0)
	s_barrier
	s_mov_b32 s5, 0x3e4ccccd
	global_load_dwordx4 v[196:199], v231, s[66:67]
	global_load_dwordx4 v[200:203], v231, s[68:69]
	global_load_dwordx4 v[32:35], v231, s[72:73]
	ds_read_b128 v[12:15], v229 offset:25088
	ds_read_b128 v[16:19], v229 offset:25152
	ds_read_b128 v[28:31], v230 offset:8704
	s_waitcnt lgkmcnt(1)
	v_mfma_f32_16x16x32_bf16 v[20:23], v[232:235], v[12:15], 0
	v_mfma_f32_16x16x32_bf16 v[24:27], v[240:243], v[12:15], 0
	v_mfma_f32_16x16x32_bf16 v[20:23], v[236:239], v[16:19], v[20:23]
	v_mfma_f32_16x16x32_bf16 v[24:27], v[244:247], v[16:19], v[24:27]
	s_waitcnt vmcnt(0)
	s_nop 7
	s_nop 3
	s_waitcnt lgkmcnt(0)
	v_add_f32_e32 v20, v20, v196
	v_add_f32_e32 v21, v21, v197
	v_add_f32_e32 v24, v24, v200
	v_add_f32_e32 v25, v25, v201
	v_mul_f32_e32 v20, 0xbfb8aa3b, v20
	v_mul_f32_e32 v21, 0xbfb8aa3b, v21
	v_mul_f32_e32 v24, 0xbfb8aa3b, v24
	v_mul_f32_e32 v25, 0xbfb8aa3b, v25
	v_exp_f32_e32 v20, v20
	v_exp_f32_e32 v21, v21
	v_exp_f32_e32 v24, v24
	v_exp_f32_e32 v25, v25
	v_add_f32_e32 v20, 1.0, v20
	v_add_f32_e32 v21, 1.0, v21
	v_add_f32_e32 v24, 1.0, v24
	v_add_f32_e32 v25, 1.0, v25
	v_rcp_f32_e32 v20, v20
	v_rcp_f32_e32 v21, v21
	v_rcp_f32_e32 v24, v24
	v_rcp_f32_e32 v25, v25
	v_pk_mul_f32 v[12:13], v[20:21], v[32:33]
	s_nop 0
	v_pk_add_f32 v[14:15], v[12:13], v[12:13]
	v_mul_f32_e32 v20, 0x3fb8aa3b, v12
	v_mul_f32_e32 v21, 0x3fb8aa3b, v13
	v_exp_f32_e32 v20, v20
	v_exp_f32_e32 v21, v21
	v_mul_f32_e32 v16, 0x3e800000, v14
	v_fma_f32 v17, v14, s5, 1.0
	v_mul_f32_e32 v18, 0x3eaaaaab, v14
	v_fma_f32 v16, v16, v17, 1.0
	v_mul_f32_e32 v17, 0.5, v14
	v_fma_f32 v18, v18, v16, 1.0
	v_fma_f32 v17, v17, v18, 1.0
	v_mul_f32_e64 v17, v17, -v14
	v_fma_f32 v16, -v20, v20, 1.0
	v_cmp_lt_f32_e32 vcc, s6, v14
	v_mul_f32_e32 v19, 0x3e800000, v15
	v_fma_f32 v12, v15, s5, 1.0
	v_cndmask_b32_e32 v16, v16, v17, vcc
	v_mul_f32_e32 v13, 0x3eaaaaab, v15
	v_fma_f32 v19, v19, v12, 1.0
	v_mul_f32_e32 v12, 0.5, v15
	v_fma_f32 v13, v13, v19, 1.0
	v_fma_f32 v12, v12, v13, 1.0
	v_mul_f32_e64 v12, v12, -v15
	v_fma_f32 v13, -v21, v21, 1.0
	v_cmp_lt_f32_e32 vcc, s6, v15
	v_sqrt_f32_e32 v16, v16
	s_nop 1
	v_cndmask_b32_e32 v17, v13, v12, vcc
	v_sqrt_f32_e32 v17, v17
	s_nop 0
	v_pk_mul_f32 v[24:25], v[24:25], v[16:17]
	s_nop 0
	v_pk_mul_f32 v[24:25], v[28:29], v[24:25]
	v_add_f32_e32 v22, v22, v198
	v_add_f32_e32 v23, v23, v199
	v_add_f32_e32 v26, v26, v202
	v_add_f32_e32 v27, v27, v203
	v_mul_f32_e32 v22, 0xbfb8aa3b, v22
	v_mul_f32_e32 v23, 0xbfb8aa3b, v23
	v_mul_f32_e32 v26, 0xbfb8aa3b, v26
	v_mul_f32_e32 v27, 0xbfb8aa3b, v27
	v_exp_f32_e32 v22, v22
	v_exp_f32_e32 v23, v23
	v_exp_f32_e32 v26, v26
	v_exp_f32_e32 v27, v27
	v_add_f32_e32 v22, 1.0, v22
	v_add_f32_e32 v23, 1.0, v23
	v_add_f32_e32 v26, 1.0, v26
	v_add_f32_e32 v27, 1.0, v27
	v_rcp_f32_e32 v22, v22
	v_rcp_f32_e32 v23, v23
	v_rcp_f32_e32 v26, v26
	v_rcp_f32_e32 v27, v27
	v_pk_mul_f32 v[12:13], v[22:23], v[34:35]
	s_nop 0
	v_pk_add_f32 v[14:15], v[12:13], v[12:13]
	v_mul_f32_e32 v22, 0x3fb8aa3b, v12
	v_mul_f32_e32 v23, 0x3fb8aa3b, v13
	v_exp_f32_e32 v22, v22
	v_exp_f32_e32 v23, v23
	v_mul_f32_e32 v16, 0x3e800000, v14
	v_fma_f32 v17, v14, s5, 1.0
	v_mul_f32_e32 v18, 0x3eaaaaab, v14
	v_fma_f32 v16, v16, v17, 1.0
	v_mul_f32_e32 v17, 0.5, v14
	v_fma_f32 v18, v18, v16, 1.0
	v_fma_f32 v17, v17, v18, 1.0
	v_mul_f32_e64 v17, v17, -v14
	v_fma_f32 v16, -v22, v22, 1.0
	v_cmp_lt_f32_e32 vcc, s6, v14
	v_mul_f32_e32 v19, 0x3e800000, v15
	v_fma_f32 v12, v15, s5, 1.0
	v_cndmask_b32_e32 v16, v16, v17, vcc
	v_mul_f32_e32 v13, 0x3eaaaaab, v15
	v_fma_f32 v19, v19, v12, 1.0
	v_mul_f32_e32 v12, 0.5, v15
	v_fma_f32 v13, v13, v19, 1.0
	v_fma_f32 v12, v12, v13, 1.0
	v_mul_f32_e64 v12, v12, -v15
	v_fma_f32 v13, -v23, v23, 1.0
	v_cmp_lt_f32_e32 vcc, s6, v15
	v_sqrt_f32_e32 v16, v16
	s_nop 1
	v_cndmask_b32_e32 v17, v13, v12, vcc
	v_sqrt_f32_e32 v17, v17
	s_nop 0
	v_pk_mul_f32 v[26:27], v[26:27], v[16:17]
	s_nop 0
	v_pk_mul_f32 v[26:27], v[30:31], v[26:27]
	ds_write_b128 v230, v[20:23] offset:34304
	ds_write_b128 v230, v[24:27] offset:50688
	ds_read_b128 v[12:15], v229 offset:27392
	ds_read_b128 v[16:19], v229 offset:27456
	ds_read_b128 v[28:31], v230 offset:12800
	s_waitcnt lgkmcnt(1)
	v_mfma_f32_16x16x32_bf16 v[20:23], v[232:235], v[12:15], 0
	v_mfma_f32_16x16x32_bf16 v[24:27], v[240:243], v[12:15], 0
	v_mfma_f32_16x16x32_bf16 v[20:23], v[236:239], v[16:19], v[20:23]
	v_mfma_f32_16x16x32_bf16 v[24:27], v[244:247], v[16:19], v[24:27]
	s_nop 7
	s_nop 3
	s_waitcnt lgkmcnt(0)
; __device__ __forceinline__ float sigmoidf_(float x) { return __builtin_amdgcn_rcpf(1.0f + __expf(-x)); }
; template <bool FINAL>
; __device__ void phase_lru(const Params& p, int l, unsigned char* smem) {
;     ...
;       {
;         bf16x8 uf[2];
;         uf[0] = *(const bf16x8*)(ub + (16 * w + l15) * 72 + g * 8);
;         uf[1] = *(const bf16x8*)(ub + (16 * w + l15) * 72 + 32 + g * 8);
;         const int t = 16 * w + l15;
; #pragma unroll
;         for (int et = 0; et < 4; ++et) {
;           f32x4 ar = {0.f, 0.f, 0.f, 0.f}, ai = {0.f, 0.f, 0.f, 0.f};
;           const u16* wr = p.WLRU + ((((size_t)(l * 2 + d) * 2 + 0) * 8 + nb) * 64 + et * 16 + l15) * 64 + g * 8;
;           const u16* wi = p.WLRU + ((((size_t)(l * 2 + d) * 2 + 1) * 8 + nb) * 64 + et * 16 + l15) * 64 + g * 8;
; #pragma unroll
;           for (int ks = 0; ks < 2; ++ks) {
;             ar = mfma16(*(const bf16x8*)(wr + ks * 32), uf[ks], ar);
;             ai = mfma16(*(const bf16x8*)(wi + ks * 32), uf[ks], ai);
;           }
;           const int e0 = et * 16 + 4 * g, ch0 = nb * 64 + e0;
;           const float4 ba4 = *(const float4*)(p.ba + (l * 2 + d) * 512 + ch0);
;           const float4 bx4 = *(const float4*)(p.bx + (l * 2 + d) * 512 + ch0);
;           const float4 sp4 = *(const float4*)(p.SP8 + (l * 2 + d) * 512 + ch0);
;           const float4 uu = *(const float4*)(u32 + t * 64 + e0);
;           const float* bap = (const float*)&ba4; const float* bxp = (const float*)&bx4;
;           const float* spp = (const float*)&sp4; const float* uup = (const float*)&uu;
;           f32x4 av, bv;
; #pragma unroll
;           for (int j = 0; j < 4; ++j) {
;             float r = sigmoidf_(ar[j] + bap[j]);
;             float ig = sigmoidf_(ai[j] + bxp[j]);
;             float la = spp[j] * r;
;             float av_ = __expf(la);
;             float t2 = 2.0f * la;
;             float ser = -t2 * (1.f + t2 * 0.5f * (1.f + t2 * (1.f / 3.f) * (1.f + t2 * 0.25f * (1.f + t2 * 0.2f))));
;             float om = (t2 > -0.25f) ? ser : (1.0f - av_ * av_);
;             av[j] = av_;
;             bv[j] = __builtin_amdgcn_sqrtf(om) * ig * uup[j];
;           }
;           *(f32x4*)(sa + t * 64 + e0) = av;
;           *(f32x4*)(sb + t * 64 + e0) = bv;
;         }
;       }
	v_add_f32_e32 v20, v20, v196
	v_add_f32_e32 v21, v21, v197
	v_add_f32_e32 v24, v24, v200
	v_add_f32_e32 v25, v25, v201
	v_mul_f32_e32 v20, 0xbfb8aa3b, v20
	v_mul_f32_e32 v21, 0xbfb8aa3b, v21
	v_mul_f32_e32 v24, 0xbfb8aa3b, v24
	v_mul_f32_e32 v25, 0xbfb8aa3b, v25
	v_exp_f32_e32 v20, v20
	v_exp_f32_e32 v21, v21
	v_exp_f32_e32 v24, v24
	v_exp_f32_e32 v25, v25
	v_add_f32_e32 v20, 1.0, v20
	v_add_f32_e32 v21, 1.0, v21
	v_add_f32_e32 v24, 1.0, v24
	v_add_f32_e32 v25, 1.0, v25
	v_rcp_f32_e32 v20, v20
	v_rcp_f32_e32 v21, v21
	v_rcp_f32_e32 v24, v24
	v_rcp_f32_e32 v25, v25
	v_pk_mul_f32 v[12:13], v[20:21], v[32:33]
	s_nop 0
	v_pk_add_f32 v[14:15], v[12:13], v[12:13]
	v_mul_f32_e32 v20, 0x3fb8aa3b, v12
	v_mul_f32_e32 v21, 0x3fb8aa3b, v13
	v_exp_f32_e32 v20, v20
	v_exp_f32_e32 v21, v21
	v_mul_f32_e32 v16, 0x3e800000, v14
	v_fma_f32 v17, v14, s5, 1.0
	v_mul_f32_e32 v18, 0x3eaaaaab, v14
	v_fma_f32 v16, v16, v17, 1.0
	v_mul_f32_e32 v17, 0.5, v14
	v_fma_f32 v18, v18, v16, 1.0
	v_fma_f32 v17, v17, v18, 1.0
	v_mul_f32_e64 v17, v17, -v14
	v_fma_f32 v16, -v20, v20, 1.0
	v_cmp_lt_f32_e32 vcc, s6, v14
	v_mul_f32_e32 v19, 0x3e800000, v15
	v_fma_f32 v12, v15, s5, 1.0
	v_cndmask_b32_e32 v16, v16, v17, vcc
	v_mul_f32_e32 v13, 0x3eaaaaab, v15
	v_fma_f32 v19, v19, v12, 1.0
	v_mul_f32_e32 v12, 0.5, v15
	v_fma_f32 v13, v13, v19, 1.0
	v_fma_f32 v12, v12, v13, 1.0
	v_mul_f32_e64 v12, v12, -v15
	v_fma_f32 v13, -v21, v21, 1.0
	v_cmp_lt_f32_e32 vcc, s6, v15
	v_sqrt_f32_e32 v16, v16
	s_nop 1
	v_cndmask_b32_e32 v17, v13, v12, vcc
	v_sqrt_f32_e32 v17, v17
	s_nop 0
	v_pk_mul_f32 v[24:25], v[24:25], v[16:17]
	s_nop 0
	v_pk_mul_f32 v[24:25], v[28:29], v[24:25]
	v_add_f32_e32 v22, v22, v198
	v_add_f32_e32 v23, v23, v199
	v_add_f32_e32 v26, v26, v202
	v_add_f32_e32 v27, v27, v203
	v_mul_f32_e32 v22, 0xbfb8aa3b, v22
	v_mul_f32_e32 v23, 0xbfb8aa3b, v23
	v_mul_f32_e32 v26, 0xbfb8aa3b, v26
	v_mul_f32_e32 v27, 0xbfb8aa3b, v27
	v_exp_f32_e32 v22, v22
	v_exp_f32_e32 v23, v23
	v_exp_f32_e32 v26, v26
	v_exp_f32_e32 v27, v27
	v_add_f32_e32 v22, 1.0, v22
	v_add_f32_e32 v23, 1.0, v23
	v_add_f32_e32 v26, 1.0, v26
	v_add_f32_e32 v27, 1.0, v27
	v_rcp_f32_e32 v22, v22
	v_rcp_f32_e32 v23, v23
	v_rcp_f32_e32 v26, v26
	v_rcp_f32_e32 v27, v27
	v_pk_mul_f32 v[12:13], v[22:23], v[34:35]
	s_nop 0
	v_pk_add_f32 v[14:15], v[12:13], v[12:13]
	v_mul_f32_e32 v22, 0x3fb8aa3b, v12
	v_mul_f32_e32 v23, 0x3fb8aa3b, v13
	v_exp_f32_e32 v22, v22
	v_exp_f32_e32 v23, v23
	v_mul_f32_e32 v16, 0x3e800000, v14
	v_fma_f32 v17, v14, s5, 1.0
	v_mul_f32_e32 v18, 0x3eaaaaab, v14
	v_fma_f32 v16, v16, v17, 1.0
	v_mul_f32_e32 v17, 0.5, v14
	v_fma_f32 v18, v18, v16, 1.0
	v_fma_f32 v17, v17, v18, 1.0
	v_mul_f32_e64 v17, v17, -v14
	v_fma_f32 v16, -v22, v22, 1.0
	v_cmp_lt_f32_e32 vcc, s6, v14
	v_mul_f32_e32 v19, 0x3e800000, v15
	v_fma_f32 v12, v15, s5, 1.0
	v_cndmask_b32_e32 v16, v16, v17, vcc
	v_mul_f32_e32 v13, 0x3eaaaaab, v15
	v_fma_f32 v19, v19, v12, 1.0
	v_mul_f32_e32 v12, 0.5, v15
	v_fma_f32 v13, v13, v19, 1.0
	v_fma_f32 v12, v12, v13, 1.0
	v_mul_f32_e64 v12, v12, -v15
	v_fma_f32 v13, -v23, v23, 1.0
	v_cmp_lt_f32_e32 vcc, s6, v15
	v_sqrt_f32_e32 v16, v16
	s_nop 1
	v_cndmask_b32_e32 v17, v13, v12, vcc
	v_sqrt_f32_e32 v17, v17
	s_nop 0
	v_pk_mul_f32 v[26:27], v[26:27], v[16:17]
	s_nop 0
	v_pk_mul_f32 v[26:27], v[30:31], v[26:27]
	ds_write_b128 v230, v[20:23] offset:38400
	ds_write_b128 v230, v[24:27] offset:54784
	ds_read_b128 v[12:15], v229 offset:29696
	ds_read_b128 v[16:19], v229 offset:29760
	ds_read_b128 v[28:31], v230 offset:16896
	s_waitcnt lgkmcnt(1)
	v_mfma_f32_16x16x32_bf16 v[20:23], v[232:235], v[12:15], 0
	v_mfma_f32_16x16x32_bf16 v[24:27], v[240:243], v[12:15], 0
	v_mfma_f32_16x16x32_bf16 v[20:23], v[236:239], v[16:19], v[20:23]
	v_mfma_f32_16x16x32_bf16 v[24:27], v[244:247], v[16:19], v[24:27]
	s_nop 7
	s_nop 3
	s_waitcnt lgkmcnt(0)
	v_add_f32_e32 v20, v20, v196
	v_add_f32_e32 v21, v21, v197
	v_add_f32_e32 v24, v24, v200
	v_add_f32_e32 v25, v25, v201
	v_mul_f32_e32 v20, 0xbfb8aa3b, v20
	v_mul_f32_e32 v21, 0xbfb8aa3b, v21
	v_mul_f32_e32 v24, 0xbfb8aa3b, v24
	v_mul_f32_e32 v25, 0xbfb8aa3b, v25
	v_exp_f32_e32 v20, v20
	v_exp_f32_e32 v21, v21
	v_exp_f32_e32 v24, v24
	v_exp_f32_e32 v25, v25
	v_add_f32_e32 v20, 1.0, v20
	v_add_f32_e32 v21, 1.0, v21
	v_add_f32_e32 v24, 1.0, v24
	v_add_f32_e32 v25, 1.0, v25
	v_rcp_f32_e32 v20, v20
	v_rcp_f32_e32 v21, v21
	v_rcp_f32_e32 v24, v24
	v_rcp_f32_e32 v25, v25
	v_pk_mul_f32 v[12:13], v[20:21], v[32:33]
	s_nop 0
	v_pk_add_f32 v[14:15], v[12:13], v[12:13]
	v_mul_f32_e32 v20, 0x3fb8aa3b, v12
	v_mul_f32_e32 v21, 0x3fb8aa3b, v13
	v_exp_f32_e32 v20, v20
	v_exp_f32_e32 v21, v21
	v_mul_f32_e32 v16, 0x3e800000, v14
	v_fma_f32 v17, v14, s5, 1.0
	v_mul_f32_e32 v18, 0x3eaaaaab, v14
	v_fma_f32 v16, v16, v17, 1.0
	v_mul_f32_e32 v17, 0.5, v14
	v_fma_f32 v18, v18, v16, 1.0
	v_fma_f32 v17, v17, v18, 1.0
	v_mul_f32_e64 v17, v17, -v14
	v_fma_f32 v16, -v20, v20, 1.0
	v_cmp_lt_f32_e32 vcc, s6, v14
	v_mul_f32_e32 v19, 0x3e800000, v15
	v_fma_f32 v12, v15, s5, 1.0
	v_cndmask_b32_e32 v16, v16, v17, vcc
	v_mul_f32_e32 v13, 0x3eaaaaab, v15
	v_fma_f32 v19, v19, v12, 1.0
	v_mul_f32_e32 v12, 0.5, v15
	v_fma_f32 v13, v13, v19, 1.0
	v_fma_f32 v12, v12, v13, 1.0
	v_mul_f32_e64 v12, v12, -v15
	v_fma_f32 v13, -v21, v21, 1.0
	v_cmp_lt_f32_e32 vcc, s6, v15
	v_sqrt_f32_e32 v16, v16
	s_nop 1
	v_cndmask_b32_e32 v17, v13, v12, vcc
	v_sqrt_f32_e32 v17, v17
	s_nop 0
	v_pk_mul_f32 v[24:25], v[24:25], v[16:17]
	s_nop 0
	v_pk_mul_f32 v[24:25], v[28:29], v[24:25]
	v_add_f32_e32 v22, v22, v198
	v_add_f32_e32 v23, v23, v199
	v_add_f32_e32 v26, v26, v202
	v_add_f32_e32 v27, v27, v203
	v_mul_f32_e32 v22, 0xbfb8aa3b, v22
; __device__ __forceinline__ float sigmoidf_(float x) { return __builtin_amdgcn_rcpf(1.0f + __expf(-x)); }
; template <bool FINAL>
; __device__ void phase_lru(const Params& p, int l, unsigned char* smem) {
;     ...
;       {
;         bf16x8 uf[2];
;         uf[0] = *(const bf16x8*)(ub + (16 * w + l15) * 72 + g * 8);
;         uf[1] = *(const bf16x8*)(ub + (16 * w + l15) * 72 + 32 + g * 8);
;         const int t = 16 * w + l15;
; #pragma unroll
;         for (int et = 0; et < 4; ++et) {
;           f32x4 ar = {0.f, 0.f, 0.f, 0.f}, ai = {0.f, 0.f, 0.f, 0.f};
;           const u16* wr = p.WLRU + ((((size_t)(l * 2 + d) * 2 + 0) * 8 + nb) * 64 + et * 16 + l15) * 64 + g * 8;
;           const u16* wi = p.WLRU + ((((size_t)(l * 2 + d) * 2 + 1) * 8 + nb) * 64 + et * 16 + l15) * 64 + g * 8;
; #pragma unroll
;           for (int ks = 0; ks < 2; ++ks) {
;             ar = mfma16(*(const bf16x8*)(wr + ks * 32), uf[ks], ar);
;             ai = mfma16(*(const bf16x8*)(wi + ks * 32), uf[ks], ai);
;           }
;           const int e0 = et * 16 + 4 * g, ch0 = nb * 64 + e0;
;           const float4 ba4 = *(const float4*)(p.ba + (l * 2 + d) * 512 + ch0);
;           const float4 bx4 = *(const float4*)(p.bx + (l * 2 + d) * 512 + ch0);
;           const float4 sp4 = *(const float4*)(p.SP8 + (l * 2 + d) * 512 + ch0);
;           const float4 uu = *(const float4*)(u32 + t * 64 + e0);
;           const float* bap = (const float*)&ba4; const float* bxp = (const float*)&bx4;
;           const float* spp = (const float*)&sp4; const float* uup = (const float*)&uu;
;           f32x4 av, bv;
; #pragma unroll
;           for (int j = 0; j < 4; ++j) {
;             float r = sigmoidf_(ar[j] + bap[j]);
;             float ig = sigmoidf_(ai[j] + bxp[j]);
;             float la = spp[j] * r;
;             float av_ = __expf(la);
;             float t2 = 2.0f * la;
;             float ser = -t2 * (1.f + t2 * 0.5f * (1.f + t2 * (1.f / 3.f) * (1.f + t2 * 0.25f * (1.f + t2 * 0.2f))));
;             float om = (t2 > -0.25f) ? ser : (1.0f - av_ * av_);
;             av[j] = av_;
;             bv[j] = __builtin_amdgcn_sqrtf(om) * ig * uup[j];
;           }
;           *(f32x4*)(sa + t * 64 + e0) = av;
;           *(f32x4*)(sb + t * 64 + e0) = bv;
;         }
;       }
;       __syncthreads();
	v_mul_f32_e32 v23, 0xbfb8aa3b, v23
	v_mul_f32_e32 v26, 0xbfb8aa3b, v26
	v_mul_f32_e32 v27, 0xbfb8aa3b, v27
	v_exp_f32_e32 v22, v22
	v_exp_f32_e32 v23, v23
	v_exp_f32_e32 v26, v26
	v_exp_f32_e32 v27, v27
	v_add_f32_e32 v22, 1.0, v22
	v_add_f32_e32 v23, 1.0, v23
	v_add_f32_e32 v26, 1.0, v26
	v_add_f32_e32 v27, 1.0, v27
	v_rcp_f32_e32 v22, v22
	v_rcp_f32_e32 v23, v23
	v_rcp_f32_e32 v26, v26
	v_rcp_f32_e32 v27, v27
	v_pk_mul_f32 v[12:13], v[22:23], v[34:35]
	s_nop 0
	v_pk_add_f32 v[14:15], v[12:13], v[12:13]
	v_mul_f32_e32 v22, 0x3fb8aa3b, v12
	v_mul_f32_e32 v23, 0x3fb8aa3b, v13
	v_exp_f32_e32 v22, v22
	v_exp_f32_e32 v23, v23
	v_mul_f32_e32 v16, 0x3e800000, v14
	v_fma_f32 v17, v14, s5, 1.0
	v_mul_f32_e32 v18, 0x3eaaaaab, v14
	v_fma_f32 v16, v16, v17, 1.0
	v_mul_f32_e32 v17, 0.5, v14
	v_fma_f32 v18, v18, v16, 1.0
	v_fma_f32 v17, v17, v18, 1.0
	v_mul_f32_e64 v17, v17, -v14
	v_fma_f32 v16, -v22, v22, 1.0
	v_cmp_lt_f32_e32 vcc, s6, v14
	v_mul_f32_e32 v19, 0x3e800000, v15
	v_fma_f32 v12, v15, s5, 1.0
	v_cndmask_b32_e32 v16, v16, v17, vcc
	v_mul_f32_e32 v13, 0x3eaaaaab, v15
	v_fma_f32 v19, v19, v12, 1.0
	v_mul_f32_e32 v12, 0.5, v15
	v_fma_f32 v13, v13, v19, 1.0
	v_fma_f32 v12, v12, v13, 1.0
	v_mul_f32_e64 v12, v12, -v15
	v_fma_f32 v13, -v23, v23, 1.0
	v_cmp_lt_f32_e32 vcc, s6, v15
	v_sqrt_f32_e32 v16, v16
	s_nop 1
	v_cndmask_b32_e32 v17, v13, v12, vcc
	v_sqrt_f32_e32 v17, v17
	s_nop 0
	v_pk_mul_f32 v[26:27], v[26:27], v[16:17]
	s_nop 0
	v_pk_mul_f32 v[26:27], v[30:31], v[26:27]
	ds_write_b128 v230, v[20:23] offset:42496
	ds_write_b128 v230, v[24:27] offset:58880
	ds_read_b128 v[12:15], v229 offset:32000
	ds_read_b128 v[16:19], v229 offset:32064
	ds_read_b128 v[28:31], v230 offset:20992
	s_waitcnt lgkmcnt(1)
	v_mfma_f32_16x16x32_bf16 v[20:23], v[232:235], v[12:15], 0
	v_mfma_f32_16x16x32_bf16 v[24:27], v[240:243], v[12:15], 0
	v_mfma_f32_16x16x32_bf16 v[20:23], v[236:239], v[16:19], v[20:23]
	v_mfma_f32_16x16x32_bf16 v[24:27], v[244:247], v[16:19], v[24:27]
	s_nop 7
	s_nop 3
	s_waitcnt lgkmcnt(0)
	v_add_f32_e32 v20, v20, v196
	v_add_f32_e32 v21, v21, v197
	v_add_f32_e32 v24, v24, v200
	v_add_f32_e32 v25, v25, v201
	v_mul_f32_e32 v20, 0xbfb8aa3b, v20
	v_mul_f32_e32 v21, 0xbfb8aa3b, v21
	v_mul_f32_e32 v24, 0xbfb8aa3b, v24
	v_mul_f32_e32 v25, 0xbfb8aa3b, v25
	v_exp_f32_e32 v20, v20
	v_exp_f32_e32 v21, v21
	v_exp_f32_e32 v24, v24
	v_exp_f32_e32 v25, v25
	v_add_f32_e32 v20, 1.0, v20
	v_add_f32_e32 v21, 1.0, v21
	v_add_f32_e32 v24, 1.0, v24
	v_add_f32_e32 v25, 1.0, v25
	v_rcp_f32_e32 v20, v20
	v_rcp_f32_e32 v21, v21
	v_rcp_f32_e32 v24, v24
	v_rcp_f32_e32 v25, v25
	v_pk_mul_f32 v[12:13], v[20:21], v[32:33]
	s_nop 0
	v_pk_add_f32 v[14:15], v[12:13], v[12:13]
	v_mul_f32_e32 v20, 0x3fb8aa3b, v12
	v_mul_f32_e32 v21, 0x3fb8aa3b, v13
	v_exp_f32_e32 v20, v20
	v_exp_f32_e32 v21, v21
	v_mul_f32_e32 v16, 0x3e800000, v14
	v_fma_f32 v17, v14, s5, 1.0
	v_mul_f32_e32 v18, 0x3eaaaaab, v14
	v_fma_f32 v16, v16, v17, 1.0
	v_mul_f32_e32 v17, 0.5, v14
	v_fma_f32 v18, v18, v16, 1.0
	v_fma_f32 v17, v17, v18, 1.0
	v_mul_f32_e64 v17, v17, -v14
	v_fma_f32 v16, -v20, v20, 1.0
	v_cmp_lt_f32_e32 vcc, s6, v14
	v_mul_f32_e32 v19, 0x3e800000, v15
	v_fma_f32 v12, v15, s5, 1.0
	v_cndmask_b32_e32 v16, v16, v17, vcc
	v_mul_f32_e32 v13, 0x3eaaaaab, v15
	v_fma_f32 v19, v19, v12, 1.0
	v_mul_f32_e32 v12, 0.5, v15
	v_fma_f32 v13, v13, v19, 1.0
	v_fma_f32 v12, v12, v13, 1.0
	v_mul_f32_e64 v12, v12, -v15
	v_fma_f32 v13, -v21, v21, 1.0
	v_cmp_lt_f32_e32 vcc, s6, v15
	v_sqrt_f32_e32 v16, v16
	s_nop 1
	v_cndmask_b32_e32 v17, v13, v12, vcc
	v_sqrt_f32_e32 v17, v17
	s_nop 0
	v_pk_mul_f32 v[24:25], v[24:25], v[16:17]
	s_nop 0
	v_pk_mul_f32 v[24:25], v[28:29], v[24:25]
	v_add_f32_e32 v22, v22, v198
	v_add_f32_e32 v23, v23, v199
	v_add_f32_e32 v26, v26, v202
	v_add_f32_e32 v27, v27, v203
	v_mul_f32_e32 v22, 0xbfb8aa3b, v22
	v_mul_f32_e32 v23, 0xbfb8aa3b, v23
	v_mul_f32_e32 v26, 0xbfb8aa3b, v26
	v_mul_f32_e32 v27, 0xbfb8aa3b, v27
	v_exp_f32_e32 v22, v22
	v_exp_f32_e32 v23, v23
	v_exp_f32_e32 v26, v26
	v_exp_f32_e32 v27, v27
	v_add_f32_e32 v22, 1.0, v22
	v_add_f32_e32 v23, 1.0, v23
	v_add_f32_e32 v26, 1.0, v26
	v_add_f32_e32 v27, 1.0, v27
	v_rcp_f32_e32 v22, v22
	v_rcp_f32_e32 v23, v23
	v_rcp_f32_e32 v26, v26
	v_rcp_f32_e32 v27, v27
	v_pk_mul_f32 v[12:13], v[22:23], v[34:35]
	s_nop 0
	v_pk_add_f32 v[14:15], v[12:13], v[12:13]
	v_mul_f32_e32 v22, 0x3fb8aa3b, v12
	v_mul_f32_e32 v23, 0x3fb8aa3b, v13
	v_exp_f32_e32 v22, v22
	v_exp_f32_e32 v23, v23
	v_mul_f32_e32 v16, 0x3e800000, v14
	v_fma_f32 v17, v14, s5, 1.0
	v_mul_f32_e32 v18, 0x3eaaaaab, v14
	v_fma_f32 v16, v16, v17, 1.0
	v_mul_f32_e32 v17, 0.5, v14
	v_fma_f32 v18, v18, v16, 1.0
	v_fma_f32 v17, v17, v18, 1.0
	v_mul_f32_e64 v17, v17, -v14
	v_fma_f32 v16, -v22, v22, 1.0
	v_cmp_lt_f32_e32 vcc, s6, v14
	v_mul_f32_e32 v19, 0x3e800000, v15
	v_fma_f32 v12, v15, s5, 1.0
	v_cndmask_b32_e32 v16, v16, v17, vcc
	v_mul_f32_e32 v13, 0x3eaaaaab, v15
	v_fma_f32 v19, v19, v12, 1.0
	v_mul_f32_e32 v12, 0.5, v15
	v_fma_f32 v13, v13, v19, 1.0
	v_fma_f32 v12, v12, v13, 1.0
	v_mul_f32_e64 v12, v12, -v15
	v_fma_f32 v13, -v23, v23, 1.0
	v_cmp_lt_f32_e32 vcc, s6, v15
	v_sqrt_f32_e32 v16, v16
	s_nop 1
	v_cndmask_b32_e32 v17, v13, v12, vcc
	v_sqrt_f32_e32 v17, v17
	s_nop 0
	v_pk_mul_f32 v[26:27], v[26:27], v[16:17]
	s_nop 0
	v_pk_mul_f32 v[26:27], v[30:31], v[26:27]
	ds_write_b128 v230, v[20:23] offset:46592
	ds_write_b128 v230, v[24:27] offset:62976
	s_waitcnt lgkmcnt(0)
	s_barrier
; template <bool FINAL>
; __device__ void phase_lru(const Params& p, int l, unsigned char* smem) {
;     ...
;       {
;         float A = 1.f, B = 0.f;
;         if (d == 0) {
; #pragma unroll
;           for (int tt = 0; tt < 16; ++tt) { int t = qd * 16 + tt; float a = sa[t * 64 + e_], b = sb[t * 64 + e_]; B = a * B + b; A *= a; }
;         } else {
; #pragma unroll
;     ...
;         }
;         part[(0 * 4 + qd) * 64 + e_] = A;
;         part[(1 * 4 + qd) * 64 + e_] = B;
;       }
;       __syncthreads();
	ds_read2st64_b32 v[12:13], v132 offset0:134 offset1:198
	ds_read2st64_b32 v[14:15], v131 offset0:134 offset1:198
	ds_read2st64_b32 v[16:17], v130 offset0:134 offset1:198
	ds_read2st64_b32 v[62:63], v120 offset0:134 offset1:198
	ds_read2st64_b32 v[164:165], v119 offset0:134 offset1:198
	s_waitcnt lgkmcnt(4)
	v_fmac_f32_e32 v13, 0, v12
	s_waitcnt lgkmcnt(3)
	v_mul_f32_e32 v18, v12, v14
	s_waitcnt lgkmcnt(2)
	v_mul_f32_e32 v20, v18, v16
	ds_read2st64_b32 v[18:19], v129 offset0:134 offset1:198
	v_fmac_f32_e32 v15, v14, v13
	v_fmac_f32_e32 v17, v16, v15
	ds_read2st64_b32 v[166:167], v118 offset0:134 offset1:198
	ds_read2st64_b32 v[168:169], v59 offset0:134 offset1:198
	s_waitcnt lgkmcnt(2)
	v_mul_f32_e32 v22, v20, v18
	ds_read2st64_b32 v[20:21], v128 offset0:134 offset1:198
	v_fmac_f32_e32 v19, v18, v17
	s_waitcnt lgkmcnt(0)
	v_mul_f32_e32 v24, v22, v20
	ds_read2st64_b32 v[22:23], v127 offset0:134 offset1:198
	v_fmac_f32_e32 v21, v20, v19
	s_waitcnt lgkmcnt(0)
	v_mul_f32_e32 v26, v24, v22
	ds_read2st64_b32 v[24:25], v126 offset0:134 offset1:198
	v_fmac_f32_e32 v23, v22, v21
	s_waitcnt lgkmcnt(0)
	v_mul_f32_e32 v28, v26, v24
	ds_read2st64_b32 v[26:27], v125 offset0:134 offset1:198
	v_fmac_f32_e32 v25, v24, v23
	s_waitcnt lgkmcnt(0)
	v_mul_f32_e32 v30, v28, v26
	ds_read2st64_b32 v[28:29], v124 offset0:134 offset1:198
	v_fmac_f32_e32 v27, v26, v25
	s_waitcnt lgkmcnt(0)
	v_mul_f32_e32 v32, v30, v28
	ds_read2st64_b32 v[30:31], v123 offset0:134 offset1:198
	v_fmac_f32_e32 v29, v28, v27
	s_waitcnt lgkmcnt(0)
	v_mul_f32_e32 v34, v32, v30
	ds_read2st64_b32 v[32:33], v122 offset0:134 offset1:198
	v_fmac_f32_e32 v31, v30, v29
	s_waitcnt lgkmcnt(0)
	v_mul_f32_e32 v61, v34, v32
	ds_read2st64_b32 v[34:35], v121 offset0:134 offset1:198
	v_fmac_f32_e32 v33, v32, v31
	s_waitcnt lgkmcnt(0)
	v_mul_f32_e32 v61, v61, v34
	v_mul_f32_e32 v61, v61, v62
	v_fmac_f32_e32 v35, v34, v33
	v_mul_f32_e32 v61, v61, v164
	v_fmac_f32_e32 v63, v62, v35
	v_mul_f32_e32 v61, v61, v166
	v_fmac_f32_e32 v165, v164, v63
	v_mul_f32_e32 v61, v61, v168
	v_fmac_f32_e32 v167, v166, v165
	v_fmac_f32_e32 v169, v168, v167
	ds_write_b32 v98, v61
	ds_write_b32 v100, v169 offset:1024
	s_waitcnt lgkmcnt(0)
	s_barrier
	s_and_saveexec_b64 s[56:57], s[48:49]
	s_cbranch_execnz .LBB0_221
	s_or_b64 exec, exec, s[56:57]
	s_and_saveexec_b64 s[56:57], s[50:51]
	s_cbranch_execnz .LBB0_222
